# v55: v53 + attention loops: canonicalising self-max triples folded into one v_max, row-sum chains no longer start with 0 + p
# speedup vs baseline: 1.0157x; 1.0023x over previous
; #define LAS __attribute__((address_space(3)))
; template <int DK, bool IS_A>
; __device__ __forceinline__ void attn_unit(const Params& P, int l, LAS unsigned char* lds, int b, int grp, int qtok0, int nkeys) {
;     ...
;             __builtin_amdgcn_s_setprio(1);
; #pragma unroll
;             for (int i = 0; i < DK / 16; ++i)
; #pragma unroll
;                 for (int jj = 0; jj < 2; ++jj) {
;                     const bf16x8 kf = *(const LAS bf16x8*)(kb + jj * 32 * AK_PITCH + i * 32);
;                     pa[jj] = __builtin_amdgcn_mfma_f32_32x32x16_bf16(kf, qa[i], pa[jj], 0, 0, 0);
;                     pb[jj] = __builtin_amdgcn_mfma_f32_32x32x16_bf16(kf, qb[i], pb[jj], 0, 0, 0);
;                 }
;             __builtin_amdgcn_s_setprio(0);
;     ...
;             AT_SOFTMAX(pa, ma, la, oa0, oa1);
;             AT_SOFTMAX(pb, mb, lb_, ob0, ob1);
.LBB0_386:
	s_bitcmp1_b32 s12, 0
	s_cselect_b32 s10, 0x8a00, 0
	s_add_i32 s10, s10, 0
	v_add_u32_e32 v64, s10, v176
	v_add_u32_e32 v186, v64, v178
	s_setprio 1
	ds_read_b128 v[64:67], v186
	ds_read_b128 v[188:191], v186 offset:32
	s_waitcnt lgkmcnt(1)
	v_mfma_f32_32x32x16_bf16 v[112:127], v[64:67], v[142:145], 0
	v_mfma_f32_32x32x16_bf16 v[96:111], v[64:67], v[158:161], 0
	ds_read_b128 v[64:67], v186 offset:4608
	s_waitcnt lgkmcnt(1)
	v_mfma_f32_32x32x16_bf16 v[112:127], v[188:191], v[150:153], v[112:127]
	v_mfma_f32_32x32x16_bf16 v[96:111], v[188:191], v[154:157], v[96:111]
	ds_read_b128 v[188:191], v186 offset:4640
	s_waitcnt lgkmcnt(1)
	v_mfma_f32_32x32x16_bf16 v[80:95], v[64:67], v[142:145], 0
	v_mfma_f32_32x32x16_bf16 v[64:79], v[64:67], v[158:161], 0
	s_waitcnt lgkmcnt(0)
	v_mfma_f32_32x32x16_bf16 v[80:95], v[188:191], v[150:153], v[80:95]
	v_mfma_f32_32x32x16_bf16 v[64:79], v[188:191], v[154:157], v[64:79]
	s_setprio 0
	s_nop 9
	v_max_f32_e32 v180, v112, v80
	v_max3_f32 v181, v81, v114, v82
	v_max3_f32 v180, v180, v113, v115
	v_max3_f32 v181, v181, v116, v84
	v_max3_f32 v180, v180, v83, v117
	v_max3_f32 v181, v181, v118, v86
	v_max3_f32 v180, v180, v85, v119
	v_max3_f32 v181, v181, v120, v88
	v_max3_f32 v180, v180, v87, v121
	v_max3_f32 v181, v181, v122, v90
	v_max3_f32 v180, v180, v89, v123
	v_max3_f32 v181, v181, v124, v92
	v_max3_f32 v180, v180, v91, v125
	v_max3_f32 v181, v181, v126, v94
	v_max3_f32 v180, v180, v93, v127
	v_max3_f32 v180, v180, v95, v181
	ds_bpermute_b32 v181, v163, v180
	s_waitcnt lgkmcnt(0)
	v_max3_f32 v187, v182, v180, v181
	v_add_f32_e32 v181, 0x41000000, v182
	v_cmp_gt_f32_e32 vcc, v187, v181
	s_cbranch_vccz .LBB0_388
	v_sub_f32_e32 v180, v182, v187
	v_exp_f32_e32 v180, v180
	s_nop 0
	v_pk_mul_f32 v[62:63], v[62:63], v[180:181] op_sel_hi:[1,0]
	v_pk_mul_f32 v[60:61], v[60:61], v[180:181] op_sel_hi:[1,0]
	v_pk_mul_f32 v[58:59], v[58:59], v[180:181] op_sel_hi:[1,0]
	v_pk_mul_f32 v[56:57], v[56:57], v[180:181] op_sel_hi:[1,0]
	v_pk_mul_f32 v[54:55], v[54:55], v[180:181] op_sel_hi:[1,0]
	v_pk_mul_f32 v[52:53], v[52:53], v[180:181] op_sel_hi:[1,0]
	v_pk_mul_f32 v[50:51], v[50:51], v[180:181] op_sel_hi:[1,0]
	v_pk_mul_f32 v[48:49], v[48:49], v[180:181] op_sel_hi:[1,0]
	v_pk_mul_f32 v[46:47], v[46:47], v[180:181] op_sel_hi:[1,0]
	v_pk_mul_f32 v[44:45], v[44:45], v[180:181] op_sel_hi:[1,0]
	v_pk_mul_f32 v[42:43], v[42:43], v[180:181] op_sel_hi:[1,0]
	v_pk_mul_f32 v[40:41], v[40:41], v[180:181] op_sel_hi:[1,0]
	v_pk_mul_f32 v[38:39], v[38:39], v[180:181] op_sel_hi:[1,0]
	v_pk_mul_f32 v[36:37], v[36:37], v[180:181] op_sel_hi:[1,0]
	v_pk_mul_f32 v[34:35], v[34:35], v[180:181] op_sel_hi:[1,0]
	v_pk_mul_f32 v[32:33], v[32:33], v[180:181] op_sel_hi:[1,0]
	v_mul_f32_e32 v184, v184, v180
	s_branch .LBB0_389

; template <int DK, bool IS_A>
; __device__ __forceinline__ void attn_unit(const Params& P, int l, LAS unsigned char* lds, int b, int grp, int qtok0, int nkeys) {
;     ...
;             AT_SOFTMAX(pa, ma, la, oa0, oa1);
;             AT_SOFTMAX(pb, mb, lb_, ob0, ob1);
.LBB0_389:
	v_max_f32_e32 v180, v96, v64
	v_max3_f32 v181, v65, v98, v66
	v_max3_f32 v180, v180, v97, v99
	v_max3_f32 v181, v181, v100, v68
	v_max3_f32 v180, v180, v67, v101
	v_max3_f32 v181, v181, v102, v70
	v_max3_f32 v180, v180, v69, v103
	v_max3_f32 v181, v181, v104, v72
	v_max3_f32 v180, v180, v71, v105
	v_max3_f32 v181, v181, v106, v74
	v_max3_f32 v180, v180, v73, v107
	v_max3_f32 v181, v181, v108, v76
	v_max3_f32 v180, v180, v75, v109
	v_max3_f32 v181, v181, v110, v78
	v_max3_f32 v180, v180, v77, v111
	v_max3_f32 v180, v180, v79, v181
	ds_bpermute_b32 v181, v163, v180
	s_waitcnt lgkmcnt(0)
	v_max3_f32 v185, v183, v180, v181
	v_add_f32_e32 v181, 0x41000000, v183
	v_cmp_gt_f32_e32 vcc, v185, v181
	s_cbranch_vccz .LBB0_391
	v_sub_f32_e32 v180, v183, v185
	v_exp_f32_e32 v180, v180
	s_nop 0
	v_pk_mul_f32 v[30:31], v[30:31], v[180:181] op_sel_hi:[1,0]
	v_pk_mul_f32 v[28:29], v[28:29], v[180:181] op_sel_hi:[1,0]
	v_pk_mul_f32 v[26:27], v[26:27], v[180:181] op_sel_hi:[1,0]
	v_pk_mul_f32 v[24:25], v[24:25], v[180:181] op_sel_hi:[1,0]
	v_pk_mul_f32 v[22:23], v[22:23], v[180:181] op_sel_hi:[1,0]
	v_pk_mul_f32 v[20:21], v[20:21], v[180:181] op_sel_hi:[1,0]
	v_pk_mul_f32 v[18:19], v[18:19], v[180:181] op_sel_hi:[1,0]
	v_pk_mul_f32 v[16:17], v[16:17], v[180:181] op_sel_hi:[1,0]
	v_pk_mul_f32 v[14:15], v[14:15], v[180:181] op_sel_hi:[1,0]
	v_pk_mul_f32 v[12:13], v[12:13], v[180:181] op_sel_hi:[1,0]
	v_pk_mul_f32 v[10:11], v[10:11], v[180:181] op_sel_hi:[1,0]
	v_pk_mul_f32 v[8:9], v[8:9], v[180:181] op_sel_hi:[1,0]
	v_pk_mul_f32 v[6:7], v[6:7], v[180:181] op_sel_hi:[1,0]
	v_pk_mul_f32 v[4:5], v[4:5], v[180:181] op_sel_hi:[1,0]
	v_pk_mul_f32 v[2:3], v[2:3], v[180:181] op_sel_hi:[1,0]
	v_pk_mul_f32 v[0:1], v[0:1], v[180:181] op_sel_hi:[1,0]
	v_mul_f32_e32 v179, v179, v180
	s_branch .LBB0_392

; #define LAS __attribute__((address_space(3)))
; __device__ __forceinline__ unsigned pk2(float lo, float hi) { f32x2_t v = {lo, hi}; bf16x2_t b = __builtin_convertvector(v, bf16x2_t); return __builtin_bit_cast(unsigned, b); }
; template <int DK, bool IS_A>
; __device__ __forceinline__ void attn_unit(const Params& P, int l, LAS unsigned char* lds, int b, int grp, int qtok0, int nkeys) {
;     ...
;             AT_SOFTMAX(pa, ma, la, oa0, oa1);
;             AT_SOFTMAX(pb, mb, lb_, ob0, ob1);
;     ...
; #pragma unroll
;             for (int ks = 0; ks < 4; ++ks) {
;                 const int o8 = 8 * (ks & 1);
;                 u32x4 w; const f32x16& xa = pa[ks >> 1]; const f32x16& xb = pb[ks >> 1];
;                 w.x = pk2(xa[o8], xa[o8 + 1]); w.y = pk2(xa[o8 + 2], xa[o8 + 3]); w.z = pk2(xa[o8 + 4], xa[o8 + 5]); w.w = pk2(xa[o8 + 6], xa[o8 + 7]);
;                 const bf16x8 pfa = __builtin_bit_cast(bf16x8, w);
;                 w.x = pk2(xb[o8], xb[o8 + 1]); w.y = pk2(xb[o8 + 2], xb[o8 + 3]); w.z = pk2(xb[o8 + 4], xb[o8 + 5]); w.w = pk2(xb[o8 + 6], xb[o8 + 7]);
;                 const bf16x8 pfb = __builtin_bit_cast(bf16x8, w);
;                 const u32x2 a0 = *(const LAS u32x2*)(vb + ks * 32), a1 = *(const LAS u32x2*)(vb + ks * 32 + 16);
;                 const u32x2 c0 = *(const LAS u32x2*)(vb + 32 * AV_PITCH + ks * 32), c1 = *(const LAS u32x2*)(vb + 32 * AV_PITCH + ks * 32 + 16);
;                 const bf16x8 v0 = __builtin_bit_cast(bf16x8, ((u32x4){a0.x, a0.y, a1.x, a1.y})), v1 = __builtin_bit_cast(bf16x8, ((u32x4){c0.x, c0.y, c1.x, c1.y}));
;                 oa0 = __builtin_amdgcn_mfma_f32_32x32x16_bf16(v0, pfa, oa0, 0, 0, 0);
;                 oa1 = __builtin_amdgcn_mfma_f32_32x32x16_bf16(v1, pfa, oa1, 0, 0, 0);
;                 ob0 = __builtin_amdgcn_mfma_f32_32x32x16_bf16(v0, pfb, ob0, 0, 0, 0);
;                 ob1 = __builtin_amdgcn_mfma_f32_32x32x16_bf16(v1, pfb, ob1, 0, 0, 0);
;             }
.LBB0_392:
	v_sub_f32_e32 v112, v112, v187
	v_exp_f32_e32 v112, v112
	v_sub_f32_e32 v113, v113, v187
	v_exp_f32_e32 v113, v113
	v_sub_f32_e32 v114, v114, v187
	v_exp_f32_e32 v114, v114
	v_sub_f32_e32 v115, v115, v187
	v_exp_f32_e32 v115, v115
	v_sub_f32_e32 v116, v116, v187
	v_exp_f32_e32 v116, v116
	v_sub_f32_e32 v117, v117, v187
	v_add_f32_e32 v180, v113, v112
	v_exp_f32_e32 v117, v117
	v_sub_f32_e32 v118, v118, v187
	v_add_f32_e32 v180, v114, v180
	v_exp_f32_e32 v118, v118
	v_sub_f32_e32 v119, v119, v187
	v_add_f32_e32 v180, v115, v180
	v_exp_f32_e32 v119, v119
	v_sub_f32_e32 v120, v120, v187
	v_add_f32_e32 v180, v116, v180
	v_exp_f32_e32 v120, v120
	v_sub_f32_e32 v121, v121, v187
	v_add_f32_e32 v180, v117, v180
	v_exp_f32_e32 v121, v121
	v_sub_f32_e32 v122, v122, v187
	v_add_f32_e32 v180, v118, v180
	v_exp_f32_e32 v122, v122
	v_sub_f32_e32 v123, v123, v187
	v_add_f32_e32 v180, v119, v180
	v_exp_f32_e32 v123, v123
	v_sub_f32_e32 v124, v124, v187
	v_add_f32_e32 v180, v120, v180
	v_exp_f32_e32 v124, v124
	v_sub_f32_e32 v125, v125, v187
	v_add_f32_e32 v180, v121, v180
	v_exp_f32_e32 v125, v125
	v_sub_f32_e32 v126, v126, v187
	v_add_f32_e32 v180, v122, v180
	v_exp_f32_e32 v126, v126
	v_sub_f32_e32 v127, v127, v187
	v_add_f32_e32 v180, v123, v180
	v_exp_f32_e32 v127, v127
	v_sub_f32_e32 v80, v80, v187
	v_add_f32_e32 v180, v124, v180
	v_exp_f32_e32 v182, v80
	v_sub_f32_e32 v80, v81, v187
	v_add_f32_e32 v180, v125, v180
	v_exp_f32_e32 v210, v80
	v_sub_f32_e32 v81, v82, v187
	v_add_f32_e32 v80, v126, v180
	v_exp_f32_e32 v211, v81
	v_sub_f32_e32 v81, v83, v187
	v_add_f32_e32 v80, v127, v80
	v_exp_f32_e32 v212, v81
	v_sub_f32_e32 v81, v84, v187
	v_add_f32_e32 v80, v182, v80
	v_exp_f32_e32 v213, v81
	v_sub_f32_e32 v81, v85, v187
	v_add_f32_e32 v80, v210, v80
	v_exp_f32_e32 v214, v81
	v_sub_f32_e32 v81, v86, v187
	v_add_f32_e32 v80, v211, v80
	v_exp_f32_e32 v215, v81
	v_sub_f32_e32 v81, v87, v187
	v_add_f32_e32 v80, v212, v80
	v_exp_f32_e32 v216, v81
	v_sub_f32_e32 v81, v88, v187
	v_add_f32_e32 v80, v213, v80
	v_exp_f32_e32 v217, v81
	v_sub_f32_e32 v81, v89, v187
	v_add_f32_e32 v80, v214, v80
	v_exp_f32_e32 v219, v81
	v_add_f32_e32 v80, v215, v80
	v_add_f32_e32 v80, v216, v80
	v_add_f32_e32 v80, v217, v80
	v_add_f32_e32 v223, v219, v80
	v_sub_f32_e32 v80, v90, v187
	v_exp_f32_e32 v224, v80
	v_sub_f32_e32 v80, v91, v187
	v_exp_f32_e32 v225, v80
	v_sub_f32_e32 v80, v92, v187
	v_exp_f32_e32 v92, v80
	v_add_u32_e32 v80, s10, v177
	v_sub_f32_e32 v81, v96, v185
	v_add_u32_e32 v88, v80, v164
	v_exp_f32_e32 v183, v81
	v_sub_f32_e32 v81, v97, v185
	v_add_u32_e32 v180, 0x4800, v88
	v_add_u32_e32 v181, 0x6800, v88
	v_exp_f32_e32 v188, v81
	ds_read2_b64 v[80:83], v180 offset1:2
	ds_read2_b64 v[88:91], v181 offset0:32 offset1:34
	v_sub_f32_e32 v96, v99, v185
	v_sub_f32_e32 v84, v98, v185
	v_exp_f32_e32 v190, v96
	v_sub_f32_e32 v96, v100, v185
	v_exp_f32_e32 v189, v84
	v_cvt_pk_bf16_f32 v84, v112, v113
	v_cvt_pk_bf16_f32 v85, v114, v115
	v_cvt_pk_bf16_f32 v86, v116, v117
	v_cvt_pk_bf16_f32 v87, v118, v119
	v_exp_f32_e32 v191, v96
	v_sub_f32_e32 v96, v101, v185
	s_waitcnt lgkmcnt(1)
	v_mfma_f32_32x32x16_bf16 v[48:63], v[80:83], v[84:87], v[48:63]
	v_exp_f32_e32 v192, v96
	v_sub_f32_e32 v96, v102, v185
	v_exp_f32_e32 v193, v96
	v_sub_f32_e32 v96, v107, v185
	v_exp_f32_e32 v198, v96
	v_sub_f32_e32 v96, v108, v185
	v_exp_f32_e32 v199, v96
	s_waitcnt lgkmcnt(0)
	v_mfma_f32_32x32x16_bf16 v[32:47], v[88:91], v[84:87], v[32:47]
	v_sub_f32_e32 v84, v103, v185
	v_exp_f32_e32 v194, v84
	v_cvt_pk_bf16_f32 v84, v183, v188
	v_cvt_pk_bf16_f32 v85, v189, v190
	v_cvt_pk_bf16_f32 v86, v191, v192
	v_cvt_pk_bf16_f32 v87, v193, v194
	v_sub_f32_e32 v96, v109, v185
	v_exp_f32_e32 v204, v96
	v_mfma_f32_32x32x16_bf16 v[16:31], v[80:83], v[84:87], v[16:31]
	v_sub_f32_e32 v80, v93, v187
	v_exp_f32_e32 v93, v80
	v_sub_f32_e32 v80, v104, v185
	v_exp_f32_e32 v195, v80
	v_sub_f32_e32 v80, v105, v185
	v_exp_f32_e32 v196, v80
	ds_read2_b64 v[80:83], v180 offset0:4 offset1:6
	v_mfma_f32_32x32x16_bf16 v[0:15], v[88:91], v[84:87], v[0:15]
	ds_read2_b64 v[88:91], v181 offset0:36 offset1:38
	v_sub_f32_e32 v84, v106, v185
	v_exp_f32_e32 v197, v84
	v_cvt_pk_bf16_f32 v84, v120, v121
	v_cvt_pk_bf16_f32 v85, v122, v123
	v_cvt_pk_bf16_f32 v86, v124, v125
	v_cvt_pk_bf16_f32 v87, v126, v127
	v_sub_f32_e32 v96, v110, v185
	v_exp_f32_e32 v205, v96
	s_waitcnt lgkmcnt(1)
	v_mfma_f32_32x32x16_bf16 v[48:63], v[80:83], v[84:87], v[48:63]
	v_sub_f32_e32 v64, v64, v185
	v_exp_f32_e32 v207, v64
	v_sub_f32_e32 v64, v65, v185
	v_exp_f32_e32 v208, v64
	v_sub_f32_e32 v64, v66, v185
	v_exp_f32_e32 v209, v64
	v_sub_f32_e32 v64, v67, v185
	s_waitcnt lgkmcnt(0)
; #define LAS __attribute__((address_space(3)))
; template <int DK, bool IS_A>
; __device__ __forceinline__ void attn_unit(const Params& P, int l, LAS unsigned char* lds, int b, int grp, int qtok0, int nkeys) {
;     ...
;             __builtin_amdgcn_s_setprio(1);
; #pragma unroll
;             for (int i = 0; i < DK / 16; ++i)
; #pragma unroll
;                 for (int jj = 0; jj < 2; ++jj) {
;                     const bf16x8 kf = *(const LAS bf16x8*)(kb + jj * 32 * AK_PITCH + i * 32);
;                     pa[jj] = __builtin_amdgcn_mfma_f32_32x32x16_bf16(kf, qa[i], pa[jj], 0, 0, 0);
;                     pb[jj] = __builtin_amdgcn_mfma_f32_32x32x16_bf16(kf, qb[i], pb[jj], 0, 0, 0);
;                 }
;             __builtin_amdgcn_s_setprio(0);
;     ...
;             AT_SOFTMAX(pa, ma, la, oa0, oa1);
;             AT_SOFTMAX(pb, mb, lb_, ob0, ob1);
;     ...
; #pragma unroll
;             for (int ks = 0; ks < 4; ++ks) {
;                 const int o8 = 8 * (ks & 1);
;                 u32x4 w; const f32x16& xa = pa[ks >> 1]; const f32x16& xb = pb[ks >> 1];
;                 w.x = pk2(xa[o8], xa[o8 + 1]); w.y = pk2(xa[o8 + 2], xa[o8 + 3]); w.z = pk2(xa[o8 + 4], xa[o8 + 5]); w.w = pk2(xa[o8 + 6], xa[o8 + 7]);
;                 const bf16x8 pfa = __builtin_bit_cast(bf16x8, w);
;                 w.x = pk2(xb[o8], xb[o8 + 1]); w.y = pk2(xb[o8 + 2], xb[o8 + 3]); w.z = pk2(xb[o8 + 4], xb[o8 + 5]); w.w = pk2(xb[o8 + 6], xb[o8 + 7]);
;                 const bf16x8 pfb = __builtin_bit_cast(bf16x8, w);
;                 const u32x2 a0 = *(const LAS u32x2*)(vb + ks * 32), a1 = *(const LAS u32x2*)(vb + ks * 32 + 16);
;                 const u32x2 c0 = *(const LAS u32x2*)(vb + 32 * AV_PITCH + ks * 32), c1 = *(const LAS u32x2*)(vb + 32 * AV_PITCH + ks * 32 + 16);
;                 const bf16x8 v0 = __builtin_bit_cast(bf16x8, ((u32x4){a0.x, a0.y, a1.x, a1.y})), v1 = __builtin_bit_cast(bf16x8, ((u32x4){c0.x, c0.y, c1.x, c1.y}));
;                 oa0 = __builtin_amdgcn_mfma_f32_32x32x16_bf16(v0, pfa, oa0, 0, 0, 0);
;                 oa1 = __builtin_amdgcn_mfma_f32_32x32x16_bf16(v1, pfa, oa1, 0, 0, 0);
;                 ob0 = __builtin_amdgcn_mfma_f32_32x32x16_bf16(v0, pfb, ob0, 0, 0, 0);
;                 ob1 = __builtin_amdgcn_mfma_f32_32x32x16_bf16(v1, pfb, ob1, 0, 0, 0);
;             }
	v_mfma_f32_32x32x16_bf16 v[32:47], v[88:91], v[84:87], v[32:47]
	v_sub_f32_e32 v84, v111, v185
	v_exp_f32_e32 v206, v84
	v_cvt_pk_bf16_f32 v84, v195, v196
	v_cvt_pk_bf16_f32 v85, v197, v198
	v_cvt_pk_bf16_f32 v86, v199, v204
	v_cvt_pk_bf16_f32 v87, v205, v206
	s_nop 1
	v_mfma_f32_32x32x16_bf16 v[16:31], v[80:83], v[84:87], v[16:31]
	v_sub_f32_e32 v80, v94, v187
	v_exp_f32_e32 v94, v80
	ds_read2_b64 v[80:83], v180 offset0:8 offset1:10
	v_mfma_f32_32x32x16_bf16 v[0:15], v[88:91], v[84:87], v[0:15]
	ds_read2_b64 v[88:91], v181 offset0:40 offset1:42
	v_cvt_pk_bf16_f32 v84, v182, v210
	v_exp_f32_e32 v210, v64
	v_sub_f32_e32 v64, v68, v185
	v_cvt_pk_bf16_f32 v85, v211, v212
	v_exp_f32_e32 v211, v64
	v_sub_f32_e32 v64, v69, v185
	v_exp_f32_e32 v212, v64
	v_sub_f32_e32 v64, v70, v185
	v_cvt_pk_bf16_f32 v86, v213, v214
	v_exp_f32_e32 v213, v64
	v_sub_f32_e32 v64, v71, v185
	v_exp_f32_e32 v214, v64
	v_cvt_pk_bf16_f32 v87, v215, v216
	v_sub_f32_e32 v68, v95, v187
	v_cvt_pk_bf16_f32 v64, v207, v208
	s_waitcnt lgkmcnt(1)
	v_mfma_f32_32x32x16_bf16 v[48:63], v[80:83], v[84:87], v[48:63]
	v_cvt_pk_bf16_f32 v65, v209, v210
	v_cvt_pk_bf16_f32 v66, v211, v212
	v_cvt_pk_bf16_f32 v67, v213, v214
	s_waitcnt lgkmcnt(0)
	v_mfma_f32_32x32x16_bf16 v[32:47], v[88:91], v[84:87], v[32:47]
	v_exp_f32_e32 v84, v68
	v_sub_f32_e32 v68, v72, v185
	v_exp_f32_e32 v215, v68
	v_sub_f32_e32 v68, v73, v185
	v_exp_f32_e32 v216, v68
	ds_read2_b64 v[68:71], v180 offset0:12 offset1:14
	v_sub_f32_e32 v72, v75, v185
	v_mfma_f32_32x32x16_bf16 v[16:31], v[80:83], v[64:67], v[16:31]
	ds_read2_b64 v[80:83], v181 offset0:44 offset1:46
	v_exp_f32_e32 v221, v72
	v_sub_f32_e32 v72, v76, v185
	v_exp_f32_e32 v222, v72
	v_sub_f32_e32 v72, v77, v185
	v_mfma_f32_32x32x16_bf16 v[0:15], v[88:91], v[64:67], v[0:15]
	v_sub_f32_e32 v64, v74, v185
	v_exp_f32_e32 v218, v64
	v_cvt_pk_bf16_f32 v64, v217, v219
	v_cvt_pk_bf16_f32 v65, v224, v225
	v_cvt_pk_bf16_f32 v66, v92, v93
	v_cvt_pk_bf16_f32 v67, v94, v84
	v_exp_f32_e32 v217, v72
	v_sub_f32_e32 v72, v78, v185
	s_waitcnt lgkmcnt(1)
	v_mfma_f32_32x32x16_bf16 v[48:63], v[68:71], v[64:67], v[48:63]
	v_exp_f32_e32 v219, v72
	s_waitcnt lgkmcnt(0)
	v_mfma_f32_32x32x16_bf16 v[32:47], v[80:83], v[64:67], v[32:47]
	v_sub_f32_e32 v64, v79, v185
	v_exp_f32_e32 v220, v64
	v_cvt_pk_bf16_f32 v64, v215, v216
	v_cvt_pk_bf16_f32 v65, v218, v221
	v_cvt_pk_bf16_f32 v66, v222, v217
	v_cvt_pk_bf16_f32 v67, v219, v220
	s_nop 1
	v_mfma_f32_32x32x16_bf16 v[16:31], v[68:71], v[64:67], v[16:31]
	v_add_f32_e32 v68, v224, v223
	v_add_f32_e32 v68, v225, v68
	v_add_f32_e32 v68, v92, v68
	v_add_f32_e32 v68, v93, v68
	v_add_f32_e32 v68, v94, v68
	v_add_f32_e32 v68, v84, v68
	v_add_f32_e32 v184, v184, v68
	v_mfma_f32_32x32x16_bf16 v[0:15], v[80:83], v[64:67], v[0:15]
	s_setprio 1
	ds_read_b128 v[64:67], v186 offset:9216
	ds_read_b128 v[224:227], v186 offset:9248
	s_waitcnt lgkmcnt(1)
	v_mfma_f32_32x32x16_bf16 v[112:127], v[64:67], v[142:145], 0
	v_mfma_f32_32x32x16_bf16 v[96:111], v[64:67], v[158:161], 0
	ds_read_b128 v[64:67], v186 offset:13824
	s_waitcnt lgkmcnt(1)
	v_mfma_f32_32x32x16_bf16 v[112:127], v[224:227], v[150:153], v[112:127]
	v_mfma_f32_32x32x16_bf16 v[96:111], v[224:227], v[154:157], v[96:111]
	ds_read_b128 v[224:227], v186 offset:13856
	s_waitcnt lgkmcnt(1)
	v_mfma_f32_32x32x16_bf16 v[80:95], v[64:67], v[142:145], 0
	v_mfma_f32_32x32x16_bf16 v[64:79], v[64:67], v[158:161], 0
	s_waitcnt lgkmcnt(0)
	v_mfma_f32_32x32x16_bf16 v[80:95], v[224:227], v[150:153], v[80:95]
	v_mfma_f32_32x32x16_bf16 v[64:79], v[224:227], v[154:157], v[64:79]
	s_setprio 0
	s_nop 9
	v_max_f32_e32 v182, v112, v80
	v_max3_f32 v186, v81, v114, v82
	v_max3_f32 v182, v182, v113, v115
	v_max3_f32 v186, v186, v116, v84
	v_max3_f32 v182, v182, v83, v117
	v_max3_f32 v186, v186, v118, v86
	v_max3_f32 v182, v182, v85, v119
	v_max3_f32 v186, v186, v120, v88
	v_max3_f32 v182, v182, v87, v121
	v_max3_f32 v186, v186, v122, v90
	v_max3_f32 v182, v182, v89, v123
	v_max3_f32 v186, v186, v124, v92
	v_max3_f32 v182, v182, v91, v125
	v_max3_f32 v186, v186, v126, v94
	v_max3_f32 v182, v182, v93, v127
	v_max3_f32 v182, v182, v95, v186
	ds_bpermute_b32 v186, v163, v182
	s_waitcnt lgkmcnt(0)
	v_max3_f32 v182, v187, v182, v186
	v_add_f32_e32 v186, 0x41000000, v187
	v_cmp_gt_f32_e32 vcc, v182, v186
	s_cbranch_vccz .LBB0_394
	v_sub_f32_e32 v186, v187, v182
	v_exp_f32_e32 v186, v186
	s_nop 0
	v_pk_mul_f32 v[62:63], v[62:63], v[186:187] op_sel_hi:[1,0]
	v_pk_mul_f32 v[60:61], v[60:61], v[186:187] op_sel_hi:[1,0]
	v_pk_mul_f32 v[58:59], v[58:59], v[186:187] op_sel_hi:[1,0]
	v_pk_mul_f32 v[56:57], v[56:57], v[186:187] op_sel_hi:[1,0]
	v_pk_mul_f32 v[54:55], v[54:55], v[186:187] op_sel_hi:[1,0]
	v_pk_mul_f32 v[52:53], v[52:53], v[186:187] op_sel_hi:[1,0]
	v_pk_mul_f32 v[50:51], v[50:51], v[186:187] op_sel_hi:[1,0]
	v_pk_mul_f32 v[48:49], v[48:49], v[186:187] op_sel_hi:[1,0]
	v_pk_mul_f32 v[46:47], v[46:47], v[186:187] op_sel_hi:[1,0]
	v_pk_mul_f32 v[44:45], v[44:45], v[186:187] op_sel_hi:[1,0]
	v_pk_mul_f32 v[42:43], v[42:43], v[186:187] op_sel_hi:[1,0]
	v_pk_mul_f32 v[40:41], v[40:41], v[186:187] op_sel_hi:[1,0]
	v_pk_mul_f32 v[38:39], v[38:39], v[186:187] op_sel_hi:[1,0]
	v_pk_mul_f32 v[36:37], v[36:37], v[186:187] op_sel_hi:[1,0]
	v_pk_mul_f32 v[34:35], v[34:35], v[186:187] op_sel_hi:[1,0]
	v_pk_mul_f32 v[32:33], v[32:33], v[186:187] op_sel_hi:[1,0]
	v_mul_f32_e32 v184, v184, v186
	s_branch .LBB0_395

; template <int DK, bool IS_A>
; __device__ __forceinline__ void attn_unit(const Params& P, int l, LAS unsigned char* lds, int b, int grp, int qtok0, int nkeys) {
;     ...
;             AT_SOFTMAX(pa, ma, la, oa0, oa1);
;             AT_SOFTMAX(pb, mb, lb_, ob0, ob1);
.LBB0_395:
	v_add_f32_e32 v183, v188, v183
	v_add_f32_e32 v183, v189, v183
	v_add_f32_e32 v183, v190, v183
	v_add_f32_e32 v183, v191, v183
	v_add_f32_e32 v183, v192, v183
	v_add_f32_e32 v183, v193, v183
	v_add_f32_e32 v183, v194, v183
	v_add_f32_e32 v183, v195, v183
	v_add_f32_e32 v183, v196, v183
	v_add_f32_e32 v183, v197, v183
	v_add_f32_e32 v183, v198, v183
	v_add_f32_e32 v183, v199, v183
	v_add_f32_e32 v183, v204, v183
	v_add_f32_e32 v183, v205, v183
	v_add_f32_e32 v183, v206, v183
	v_add_f32_e32 v183, v207, v183
	v_add_f32_e32 v183, v208, v183
	v_max_f32_e32 v186, v64, v64
	v_max_f32_e32 v187, v96, v96
	v_add_f32_e32 v183, v209, v183
	v_max_f32_e32 v186, v187, v186
	v_add_f32_e32 v183, v210, v183
	v_max3_f32 v187, v65, v98, v66
	v_max3_f32 v186, v186, v97, v99
	v_add_f32_e32 v183, v211, v183
	v_max3_f32 v187, v187, v100, v68
	v_max3_f32 v186, v186, v67, v101
	v_add_f32_e32 v183, v212, v183
	v_max3_f32 v187, v187, v102, v70
	v_max3_f32 v186, v186, v69, v103
	v_add_f32_e32 v183, v213, v183
	v_max3_f32 v187, v187, v104, v72
	v_max3_f32 v186, v186, v71, v105
	v_add_f32_e32 v183, v214, v183
	v_max3_f32 v187, v187, v106, v74
	v_max3_f32 v186, v186, v73, v107
	v_add_f32_e32 v183, v215, v183
	v_max3_f32 v187, v187, v108, v76
	v_max3_f32 v186, v186, v75, v109
	v_add_f32_e32 v183, v216, v183
	v_max3_f32 v187, v187, v110, v78
	v_max3_f32 v186, v186, v77, v111
	v_add_f32_e32 v183, v218, v183
	v_max3_f32 v186, v186, v79, v187
	v_add_f32_e32 v183, v221, v183
	ds_bpermute_b32 v187, v163, v186
	v_add_f32_e32 v183, v222, v183
	v_add_f32_e32 v183, v217, v183
	v_add_f32_e32 v183, v219, v183
	v_add_f32_e32 v183, v220, v183
	v_add_f32_e32 v179, v179, v183
	s_waitcnt lgkmcnt(0)
	v_max3_f32 v183, v185, v186, v187
	v_add_f32_e32 v187, 0x41000000, v185
	v_cmp_gt_f32_e32 vcc, v183, v187
	s_cbranch_vccz .LBB0_397
	v_sub_f32_e32 v185, v185, v183
	v_exp_f32_e32 v186, v185
	s_nop 0
	v_pk_mul_f32 v[30:31], v[30:31], v[186:187] op_sel_hi:[1,0]
	v_pk_mul_f32 v[28:29], v[28:29], v[186:187] op_sel_hi:[1,0]
	v_pk_mul_f32 v[26:27], v[26:27], v[186:187] op_sel_hi:[1,0]
	v_pk_mul_f32 v[24:25], v[24:25], v[186:187] op_sel_hi:[1,0]
	v_pk_mul_f32 v[22:23], v[22:23], v[186:187] op_sel_hi:[1,0]
	v_pk_mul_f32 v[20:21], v[20:21], v[186:187] op_sel_hi:[1,0]
	v_pk_mul_f32 v[18:19], v[18:19], v[186:187] op_sel_hi:[1,0]
	v_pk_mul_f32 v[16:17], v[16:17], v[186:187] op_sel_hi:[1,0]
	v_pk_mul_f32 v[14:15], v[14:15], v[186:187] op_sel_hi:[1,0]
	v_pk_mul_f32 v[12:13], v[12:13], v[186:187] op_sel_hi:[1,0]
	v_pk_mul_f32 v[10:11], v[10:11], v[186:187] op_sel_hi:[1,0]
	v_pk_mul_f32 v[8:9], v[8:9], v[186:187] op_sel_hi:[1,0]
	v_pk_mul_f32 v[6:7], v[6:7], v[186:187] op_sel_hi:[1,0]
	v_pk_mul_f32 v[4:5], v[4:5], v[186:187] op_sel_hi:[1,0]
	v_pk_mul_f32 v[2:3], v[2:3], v[186:187] op_sel_hi:[1,0]
	v_pk_mul_f32 v[0:1], v[0:1], v[186:187] op_sel_hi:[1,0]
	v_mul_f32_e32 v179, v179, v186
	s_branch .LBB0_398

; #define LAS __attribute__((address_space(3)))
; template <int DK, bool IS_A>
; __device__ __forceinline__ void attn_unit(const Params& P, int l, LAS unsigned char* lds, int b, int grp, int qtok0, int nkeys) {
;     ...
;             __builtin_amdgcn_s_setprio(1);
; #pragma unroll
;             for (int i = 0; i < DK / 16; ++i)
; #pragma unroll
;                 for (int jj = 0; jj < 2; ++jj) {
;                     const bf16x8 kf = *(const LAS bf16x8*)(kb + jj * 32 * AK_PITCH + i * 32);
;                     pa[jj] = __builtin_amdgcn_mfma_f32_32x32x16_bf16(kf, qa[i], pa[jj], 0, 0, 0);
;                     pb[jj] = __builtin_amdgcn_mfma_f32_32x32x16_bf16(kf, qb[i], pb[jj], 0, 0, 0);
;                 }
;             __builtin_amdgcn_s_setprio(0);
;     ...
;             AT_SOFTMAX(pa, ma, la, oa0, oa1);
.LBB0_420:
	s_mov_b32 s12, s100
	v_add_u32_e32 v64, s12, v177
	v_add_u32_e32 v187, v64, v179
	s_setprio 1
	ds_read_b128 v[64:67], v187
	ds_read_b128 v[188:191], v187 offset:32
	s_waitcnt lgkmcnt(1)
	v_mfma_f32_32x32x16_bf16 v[112:127], v[64:67], v[138:141], v[236:251]
	v_mfma_f32_32x32x16_bf16 v[96:111], v[64:67], v[146:149], 0
	ds_read_b128 v[64:67], v187 offset:4608
	s_waitcnt lgkmcnt(1)
	v_mfma_f32_32x32x16_bf16 v[112:127], v[188:191], v[142:145], v[112:127]
	v_mfma_f32_32x32x16_bf16 v[96:111], v[188:191], v[150:153], v[96:111]
	ds_read_b128 v[188:191], v187 offset:4640
	s_waitcnt lgkmcnt(1)
	v_mfma_f32_32x32x16_bf16 v[80:95], v[64:67], v[138:141], v[236:251]
	v_mfma_f32_32x32x16_bf16 v[64:79], v[64:67], v[146:149], 0
	s_waitcnt lgkmcnt(0)
	v_mfma_f32_32x32x16_bf16 v[80:95], v[188:191], v[142:145], v[80:95]
	v_mfma_f32_32x32x16_bf16 v[64:79], v[188:191], v[150:153], v[64:79]
	s_setprio 0
	s_nop 9
	v_max_f32_e32 v182, v112, v80
	v_max3_f32 v183, v81, v114, v82
	v_max3_f32 v182, v182, v113, v115
	v_max3_f32 v183, v183, v116, v84
	v_max3_f32 v182, v182, v83, v117
	v_max3_f32 v183, v183, v118, v86
	v_max3_f32 v182, v182, v85, v119
	v_max3_f32 v183, v183, v120, v88
	v_max3_f32 v182, v182, v87, v121
	v_max3_f32 v183, v183, v122, v90
	v_max3_f32 v182, v182, v89, v123
	v_max3_f32 v183, v183, v124, v92
	v_max3_f32 v182, v182, v91, v125
	v_max3_f32 v183, v183, v126, v94
	v_max3_f32 v182, v182, v93, v127
	v_max3_f32 v182, v182, v95, v183
	v_sub_f32_e32 v182, v182, v236
	ds_bpermute_b32 v183, v163, v182
	s_waitcnt lgkmcnt(0)
	v_max3_f32 v188, v181, v182, v183
	v_add_f32_e32 v183, 0x41000000, v181
	v_cmp_gt_f32_e32 vcc, v188, v183
	s_cbranch_vccz .LBB0_422
	v_add_f32_e32 v183, v188, v236
	v_sub_f32_e32 v112, v112, v183
	v_sub_f32_e32 v113, v113, v183
	v_sub_f32_e32 v114, v114, v183
	v_sub_f32_e32 v115, v115, v183
	v_sub_f32_e32 v116, v116, v183
	v_sub_f32_e32 v117, v117, v183
	v_sub_f32_e32 v118, v118, v183
	v_sub_f32_e32 v119, v119, v183
	v_sub_f32_e32 v120, v120, v183
	v_sub_f32_e32 v121, v121, v183
	v_sub_f32_e32 v122, v122, v183
	v_sub_f32_e32 v123, v123, v183
	v_sub_f32_e32 v124, v124, v183
	v_sub_f32_e32 v125, v125, v183
	v_sub_f32_e32 v126, v126, v183
	v_sub_f32_e32 v127, v127, v183
	v_sub_f32_e32 v80, v80, v183
	v_sub_f32_e32 v81, v81, v183
	v_sub_f32_e32 v82, v82, v183
	v_sub_f32_e32 v83, v83, v183
	v_sub_f32_e32 v84, v84, v183
	v_sub_f32_e32 v85, v85, v183
	v_sub_f32_e32 v86, v86, v183
	v_sub_f32_e32 v87, v87, v183
	v_sub_f32_e32 v88, v88, v183
	v_sub_f32_e32 v89, v89, v183
	v_sub_f32_e32 v90, v90, v183
	v_sub_f32_e32 v91, v91, v183
	v_sub_f32_e32 v92, v92, v183
	v_sub_f32_e32 v93, v93, v183
	v_sub_f32_e32 v94, v94, v183
	v_sub_f32_e32 v95, v95, v183
	v_sub_f32_e32 v236, 0, v188
	v_sub_f32_e32 v237, 0, v188
	v_sub_f32_e32 v238, 0, v188
	v_sub_f32_e32 v239, 0, v188
	v_sub_f32_e32 v240, 0, v188
	v_sub_f32_e32 v241, 0, v188
	v_sub_f32_e32 v242, 0, v188
	v_sub_f32_e32 v243, 0, v188
	v_sub_f32_e32 v244, 0, v188
	v_sub_f32_e32 v245, 0, v188
	v_sub_f32_e32 v246, 0, v188
	v_sub_f32_e32 v247, 0, v188
	v_sub_f32_e32 v248, 0, v188
	v_sub_f32_e32 v249, 0, v188
	v_sub_f32_e32 v250, 0, v188
	v_sub_f32_e32 v251, 0, v188
	v_sub_f32_e32 v181, v181, v188
	v_exp_f32_e32 v182, v181
	s_nop 0
	v_pk_mul_f32 v[62:63], v[62:63], v[182:183] op_sel_hi:[1,0]
	v_pk_mul_f32 v[60:61], v[60:61], v[182:183] op_sel_hi:[1,0]
	v_pk_mul_f32 v[58:59], v[58:59], v[182:183] op_sel_hi:[1,0]
	v_pk_mul_f32 v[56:57], v[56:57], v[182:183] op_sel_hi:[1,0]
	v_pk_mul_f32 v[54:55], v[54:55], v[182:183] op_sel_hi:[1,0]
	v_pk_mul_f32 v[52:53], v[52:53], v[182:183] op_sel_hi:[1,0]
	v_pk_mul_f32 v[50:51], v[50:51], v[182:183] op_sel_hi:[1,0]
	v_pk_mul_f32 v[48:49], v[48:49], v[182:183] op_sel_hi:[1,0]
	v_pk_mul_f32 v[46:47], v[46:47], v[182:183] op_sel_hi:[1,0]
	v_pk_mul_f32 v[44:45], v[44:45], v[182:183] op_sel_hi:[1,0]
	v_pk_mul_f32 v[42:43], v[42:43], v[182:183] op_sel_hi:[1,0]
	v_pk_mul_f32 v[40:41], v[40:41], v[182:183] op_sel_hi:[1,0]
	v_pk_mul_f32 v[38:39], v[38:39], v[182:183] op_sel_hi:[1,0]
	v_pk_mul_f32 v[36:37], v[36:37], v[182:183] op_sel_hi:[1,0]
	v_pk_mul_f32 v[34:35], v[34:35], v[182:183] op_sel_hi:[1,0]
	v_pk_mul_f32 v[32:33], v[32:33], v[182:183] op_sel_hi:[1,0]
	v_mul_f32_e32 v185, v185, v182
	s_branch .LBB0_423

; template <int DK, bool IS_A>
; __device__ __forceinline__ void attn_unit(const Params& P, int l, LAS unsigned char* lds, int b, int grp, int qtok0, int nkeys) {
;     ...
;             AT_SOFTMAX(pa, ma, la, oa0, oa1);
;             AT_SOFTMAX(pb, mb, lb_, ob0, ob1);
.LBB0_423:
	v_max_f32_e32 v181, v96, v64
	v_max3_f32 v182, v65, v98, v66
	v_max3_f32 v181, v181, v97, v99
	v_max3_f32 v182, v182, v100, v68
	v_max3_f32 v181, v181, v67, v101
	v_max3_f32 v182, v182, v102, v70
	v_max3_f32 v181, v181, v69, v103
	v_max3_f32 v182, v182, v104, v72
	v_max3_f32 v181, v181, v71, v105
	v_max3_f32 v182, v182, v106, v74
	v_max3_f32 v181, v181, v73, v107
	v_max3_f32 v182, v182, v108, v76
	v_max3_f32 v181, v181, v75, v109
	v_max3_f32 v182, v182, v110, v78
	v_max3_f32 v181, v181, v77, v111
	v_max3_f32 v181, v181, v79, v182
	ds_bpermute_b32 v182, v163, v181
	s_waitcnt lgkmcnt(0)
	v_max3_f32 v186, v184, v181, v182
	v_add_f32_e32 v182, 0x41000000, v184
	v_cmp_gt_f32_e32 vcc, v186, v182
	s_cbranch_vccz .LBB0_425
	v_sub_f32_e32 v181, v184, v186
	v_exp_f32_e32 v182, v181
	s_nop 0
	v_pk_mul_f32 v[30:31], v[30:31], v[182:183] op_sel_hi:[1,0]
	v_pk_mul_f32 v[28:29], v[28:29], v[182:183] op_sel_hi:[1,0]
	v_pk_mul_f32 v[26:27], v[26:27], v[182:183] op_sel_hi:[1,0]
	v_pk_mul_f32 v[24:25], v[24:25], v[182:183] op_sel_hi:[1,0]
	v_pk_mul_f32 v[22:23], v[22:23], v[182:183] op_sel_hi:[1,0]
	v_pk_mul_f32 v[20:21], v[20:21], v[182:183] op_sel_hi:[1,0]
	v_pk_mul_f32 v[18:19], v[18:19], v[182:183] op_sel_hi:[1,0]
	v_pk_mul_f32 v[16:17], v[16:17], v[182:183] op_sel_hi:[1,0]
	v_pk_mul_f32 v[14:15], v[14:15], v[182:183] op_sel_hi:[1,0]
	v_pk_mul_f32 v[12:13], v[12:13], v[182:183] op_sel_hi:[1,0]
	v_pk_mul_f32 v[10:11], v[10:11], v[182:183] op_sel_hi:[1,0]
	v_pk_mul_f32 v[8:9], v[8:9], v[182:183] op_sel_hi:[1,0]
	v_pk_mul_f32 v[6:7], v[6:7], v[182:183] op_sel_hi:[1,0]
	v_pk_mul_f32 v[4:5], v[4:5], v[182:183] op_sel_hi:[1,0]
	v_pk_mul_f32 v[2:3], v[2:3], v[182:183] op_sel_hi:[1,0]
	v_pk_mul_f32 v[0:1], v[0:1], v[182:183] op_sel_hi:[1,0]
	v_mul_f32_e32 v180, v180, v182
	s_branch .LBB0_426

; #define LAS __attribute__((address_space(3)))
; __device__ __forceinline__ unsigned pk2(float lo, float hi) { f32x2_t v = {lo, hi}; bf16x2_t b = __builtin_convertvector(v, bf16x2_t); return __builtin_bit_cast(unsigned, b); }
; template <int DK, bool IS_A>
; __device__ __forceinline__ void attn_unit(const Params& P, int l, LAS unsigned char* lds, int b, int grp, int qtok0, int nkeys) {
;     ...
;             AT_SOFTMAX(pa, ma, la, oa0, oa1);
;             AT_SOFTMAX(pb, mb, lb_, ob0, ob1);
;     ...
; #pragma unroll
;             for (int ks = 0; ks < 4; ++ks) {
;                 const int o8 = 8 * (ks & 1);
;                 u32x4 w; const f32x16& xa = pa[ks >> 1]; const f32x16& xb = pb[ks >> 1];
;                 w.x = pk2(xa[o8], xa[o8 + 1]); w.y = pk2(xa[o8 + 2], xa[o8 + 3]); w.z = pk2(xa[o8 + 4], xa[o8 + 5]); w.w = pk2(xa[o8 + 6], xa[o8 + 7]);
;                 const bf16x8 pfa = __builtin_bit_cast(bf16x8, w);
;                 w.x = pk2(xb[o8], xb[o8 + 1]); w.y = pk2(xb[o8 + 2], xb[o8 + 3]); w.z = pk2(xb[o8 + 4], xb[o8 + 5]); w.w = pk2(xb[o8 + 6], xb[o8 + 7]);
;                 const bf16x8 pfb = __builtin_bit_cast(bf16x8, w);
;                 const u32x2 a0 = *(const LAS u32x2*)(vb + ks * 32), a1 = *(const LAS u32x2*)(vb + ks * 32 + 16);
;                 const u32x2 c0 = *(const LAS u32x2*)(vb + 32 * AV_PITCH + ks * 32), c1 = *(const LAS u32x2*)(vb + 32 * AV_PITCH + ks * 32 + 16);
;                 const bf16x8 v0 = __builtin_bit_cast(bf16x8, ((u32x4){a0.x, a0.y, a1.x, a1.y})), v1 = __builtin_bit_cast(bf16x8, ((u32x4){c0.x, c0.y, c1.x, c1.y}));
;                 oa0 = __builtin_amdgcn_mfma_f32_32x32x16_bf16(v0, pfa, oa0, 0, 0, 0);
;                 oa1 = __builtin_amdgcn_mfma_f32_32x32x16_bf16(v1, pfa, oa1, 0, 0, 0);
;                 ob0 = __builtin_amdgcn_mfma_f32_32x32x16_bf16(v0, pfb, ob0, 0, 0, 0);
;                 ob1 = __builtin_amdgcn_mfma_f32_32x32x16_bf16(v1, pfb, ob1, 0, 0, 0);
;             }
.LBB0_426:
	v_exp_f32_e32 v112, v112
	v_exp_f32_e32 v113, v113
	v_exp_f32_e32 v114, v114
	v_exp_f32_e32 v115, v115
	v_exp_f32_e32 v116, v116
	v_add_f32_e32 v181, v113, v112
	v_exp_f32_e32 v117, v117
	v_add_f32_e32 v181, v114, v181
	v_exp_f32_e32 v118, v118
	v_add_f32_e32 v181, v115, v181
	v_exp_f32_e32 v119, v119
	v_add_f32_e32 v181, v116, v181
	v_exp_f32_e32 v120, v120
	v_add_f32_e32 v181, v117, v181
	v_exp_f32_e32 v121, v121
	v_add_f32_e32 v181, v118, v181
	v_exp_f32_e32 v122, v122
	v_add_f32_e32 v181, v119, v181
	v_exp_f32_e32 v123, v123
	v_add_f32_e32 v181, v120, v181
	v_exp_f32_e32 v124, v124
	v_add_f32_e32 v181, v121, v181
	v_exp_f32_e32 v125, v125
	v_add_f32_e32 v181, v122, v181
	v_exp_f32_e32 v126, v126
	v_add_f32_e32 v181, v123, v181
	v_exp_f32_e32 v127, v127
	v_add_f32_e32 v181, v124, v181
	v_exp_f32_e32 v211, v80
	v_add_f32_e32 v181, v125, v181
	v_exp_f32_e32 v212, v81
	v_add_f32_e32 v80, v126, v181
	v_exp_f32_e32 v181, v82
	v_add_f32_e32 v80, v127, v80
	v_exp_f32_e32 v213, v83
	v_add_f32_e32 v80, v211, v80
	v_exp_f32_e32 v214, v84
	v_add_f32_e32 v80, v212, v80
	v_exp_f32_e32 v215, v85
	v_add_f32_e32 v80, v181, v80
	v_exp_f32_e32 v216, v86
	v_add_f32_e32 v80, v213, v80
	v_exp_f32_e32 v217, v87
	v_add_f32_e32 v80, v214, v80
	v_exp_f32_e32 v218, v88
	v_add_f32_e32 v80, v215, v80
	v_exp_f32_e32 v220, v89
	v_add_f32_e32 v80, v216, v80
	v_add_f32_e32 v80, v217, v80
	v_add_f32_e32 v80, v218, v80
	v_add_f32_e32 v224, v220, v80
	v_exp_f32_e32 v225, v90
	v_exp_f32_e32 v226, v91
	v_exp_f32_e32 v92, v92
	v_add_u32_e32 v80, s12, v178
	v_sub_f32_e32 v81, v96, v186
	v_add_u32_e32 v88, v80, v164
	v_exp_f32_e32 v184, v81
	v_sub_f32_e32 v81, v97, v186
	v_add_u32_e32 v182, 0x4800, v88
	v_add_u32_e32 v183, 0x6800, v88
	v_exp_f32_e32 v189, v81
	ds_read2_b64 v[80:83], v182 offset1:2
	ds_read2_b64 v[88:91], v183 offset0:32 offset1:34
	v_sub_f32_e32 v96, v99, v186
	v_sub_f32_e32 v84, v98, v186
	v_exp_f32_e32 v191, v96
	v_sub_f32_e32 v96, v100, v186
	v_exp_f32_e32 v190, v84
	v_cvt_pk_bf16_f32 v84, v112, v113
	v_cvt_pk_bf16_f32 v85, v114, v115
	v_cvt_pk_bf16_f32 v86, v116, v117
	v_cvt_pk_bf16_f32 v87, v118, v119
	v_exp_f32_e32 v192, v96
	v_sub_f32_e32 v96, v101, v186
	s_waitcnt lgkmcnt(1)
	v_mfma_f32_32x32x16_bf16 v[48:63], v[80:83], v[84:87], v[48:63]
	v_exp_f32_e32 v193, v96
	v_sub_f32_e32 v96, v102, v186
	v_exp_f32_e32 v194, v96
	v_sub_f32_e32 v96, v107, v186
	v_exp_f32_e32 v199, v96
	v_sub_f32_e32 v96, v108, v186
	v_exp_f32_e32 v204, v96
	s_waitcnt lgkmcnt(0)
	v_mfma_f32_32x32x16_bf16 v[32:47], v[88:91], v[84:87], v[32:47]
	v_sub_f32_e32 v84, v103, v186
	v_exp_f32_e32 v195, v84
	v_cvt_pk_bf16_f32 v84, v184, v189
	v_cvt_pk_bf16_f32 v85, v190, v191
	v_cvt_pk_bf16_f32 v86, v192, v193
	v_cvt_pk_bf16_f32 v87, v194, v195
	v_sub_f32_e32 v96, v109, v186
	v_exp_f32_e32 v205, v96
	v_mfma_f32_32x32x16_bf16 v[16:31], v[80:83], v[84:87], v[16:31]
	v_exp_f32_e32 v93, v93
	v_sub_f32_e32 v80, v104, v186
	v_exp_f32_e32 v196, v80
	v_sub_f32_e32 v80, v105, v186
	v_exp_f32_e32 v197, v80
	ds_read2_b64 v[80:83], v182 offset0:4 offset1:6
	v_mfma_f32_32x32x16_bf16 v[0:15], v[88:91], v[84:87], v[0:15]
	ds_read2_b64 v[88:91], v183 offset0:36 offset1:38
	v_sub_f32_e32 v84, v106, v186
	v_exp_f32_e32 v198, v84
	v_cvt_pk_bf16_f32 v84, v120, v121
	v_cvt_pk_bf16_f32 v85, v122, v123
	v_cvt_pk_bf16_f32 v86, v124, v125
	v_cvt_pk_bf16_f32 v87, v126, v127
	v_sub_f32_e32 v96, v110, v186
	v_exp_f32_e32 v206, v96
	s_waitcnt lgkmcnt(1)
	v_mfma_f32_32x32x16_bf16 v[48:63], v[80:83], v[84:87], v[48:63]
	v_sub_f32_e32 v64, v64, v186
	v_exp_f32_e32 v208, v64
	v_sub_f32_e32 v64, v65, v186
	v_exp_f32_e32 v209, v64
	v_sub_f32_e32 v64, v66, v186
	v_exp_f32_e32 v210, v64
	v_sub_f32_e32 v64, v67, v186
	s_waitcnt lgkmcnt(0)
	v_mfma_f32_32x32x16_bf16 v[32:47], v[88:91], v[84:87], v[32:47]
	v_sub_f32_e32 v84, v111, v186
	v_exp_f32_e32 v207, v84
	v_cvt_pk_bf16_f32 v84, v196, v197
	v_cvt_pk_bf16_f32 v85, v198, v199
	v_cvt_pk_bf16_f32 v86, v204, v205
	v_cvt_pk_bf16_f32 v87, v206, v207
	s_nop 1
	s_nop 1
	v_mfma_f32_32x32x16_bf16 v[16:31], v[80:83], v[84:87], v[16:31]
	v_exp_f32_e32 v94, v94
	ds_read2_b64 v[80:83], v182 offset0:8 offset1:10
	v_mfma_f32_32x32x16_bf16 v[0:15], v[88:91], v[84:87], v[0:15]
	ds_read2_b64 v[88:91], v183 offset0:40 offset1:42
	v_cvt_pk_bf16_f32 v84, v211, v212
	v_exp_f32_e32 v211, v64
	v_sub_f32_e32 v64, v68, v186
	v_exp_f32_e32 v212, v64
	v_sub_f32_e32 v64, v69, v186
	v_cvt_pk_bf16_f32 v85, v181, v213
	v_exp_f32_e32 v213, v64
	v_sub_f32_e32 v64, v70, v186
	v_cvt_pk_bf16_f32 v86, v214, v215
	v_exp_f32_e32 v214, v64
	v_sub_f32_e32 v64, v71, v186
	v_exp_f32_e32 v215, v64
	v_cvt_pk_bf16_f32 v87, v216, v217
	v_cvt_pk_bf16_f32 v64, v208, v209
	s_waitcnt lgkmcnt(1)
	v_mfma_f32_32x32x16_bf16 v[48:63], v[80:83], v[84:87], v[48:63]
	v_cvt_pk_bf16_f32 v65, v210, v211
	v_cvt_pk_bf16_f32 v66, v212, v213
	v_cvt_pk_bf16_f32 v67, v214, v215
	s_waitcnt lgkmcnt(0)
	v_mfma_f32_32x32x16_bf16 v[32:47], v[88:91], v[84:87], v[32:47]
	v_exp_f32_e32 v84, v95
	v_sub_f32_e32 v68, v72, v186
	v_exp_f32_e32 v216, v68
	v_sub_f32_e32 v68, v73, v186
	v_exp_f32_e32 v217, v68
	ds_read2_b64 v[68:71], v182 offset0:12 offset1:14
	v_sub_f32_e32 v72, v75, v186
	v_mfma_f32_32x32x16_bf16 v[16:31], v[80:83], v[64:67], v[16:31]
	ds_read2_b64 v[80:83], v183 offset0:44 offset1:46
	v_exp_f32_e32 v222, v72
	v_sub_f32_e32 v72, v76, v186
	v_exp_f32_e32 v223, v72
	v_sub_f32_e32 v72, v77, v186
	v_mfma_f32_32x32x16_bf16 v[0:15], v[88:91], v[64:67], v[0:15]
	v_sub_f32_e32 v64, v74, v186
	v_exp_f32_e32 v219, v64
	v_cvt_pk_bf16_f32 v64, v218, v220
	v_cvt_pk_bf16_f32 v65, v225, v226
	v_cvt_pk_bf16_f32 v66, v92, v93
	v_cvt_pk_bf16_f32 v67, v94, v84
	v_exp_f32_e32 v218, v72
	v_sub_f32_e32 v72, v78, v186
	s_waitcnt lgkmcnt(1)
; #define LAS __attribute__((address_space(3)))
; template <int DK, bool IS_A>
; __device__ __forceinline__ void attn_unit(const Params& P, int l, LAS unsigned char* lds, int b, int grp, int qtok0, int nkeys) {
;     ...
;             __builtin_amdgcn_s_setprio(1);
; #pragma unroll
;             for (int i = 0; i < DK / 16; ++i)
; #pragma unroll
;                 for (int jj = 0; jj < 2; ++jj) {
;                     const bf16x8 kf = *(const LAS bf16x8*)(kb + jj * 32 * AK_PITCH + i * 32);
;                     pa[jj] = __builtin_amdgcn_mfma_f32_32x32x16_bf16(kf, qa[i], pa[jj], 0, 0, 0);
;                     pb[jj] = __builtin_amdgcn_mfma_f32_32x32x16_bf16(kf, qb[i], pb[jj], 0, 0, 0);
;                 }
;             __builtin_amdgcn_s_setprio(0);
;     ...
;             AT_SOFTMAX(pa, ma, la, oa0, oa1);
;             AT_SOFTMAX(pb, mb, lb_, ob0, ob1);
;     ...
; #pragma unroll
;             for (int ks = 0; ks < 4; ++ks) {
;                 const int o8 = 8 * (ks & 1);
;                 u32x4 w; const f32x16& xa = pa[ks >> 1]; const f32x16& xb = pb[ks >> 1];
;                 w.x = pk2(xa[o8], xa[o8 + 1]); w.y = pk2(xa[o8 + 2], xa[o8 + 3]); w.z = pk2(xa[o8 + 4], xa[o8 + 5]); w.w = pk2(xa[o8 + 6], xa[o8 + 7]);
;                 const bf16x8 pfa = __builtin_bit_cast(bf16x8, w);
;                 w.x = pk2(xb[o8], xb[o8 + 1]); w.y = pk2(xb[o8 + 2], xb[o8 + 3]); w.z = pk2(xb[o8 + 4], xb[o8 + 5]); w.w = pk2(xb[o8 + 6], xb[o8 + 7]);
;                 const bf16x8 pfb = __builtin_bit_cast(bf16x8, w);
;                 const u32x2 a0 = *(const LAS u32x2*)(vb + ks * 32), a1 = *(const LAS u32x2*)(vb + ks * 32 + 16);
;                 const u32x2 c0 = *(const LAS u32x2*)(vb + 32 * AV_PITCH + ks * 32), c1 = *(const LAS u32x2*)(vb + 32 * AV_PITCH + ks * 32 + 16);
;                 const bf16x8 v0 = __builtin_bit_cast(bf16x8, ((u32x4){a0.x, a0.y, a1.x, a1.y})), v1 = __builtin_bit_cast(bf16x8, ((u32x4){c0.x, c0.y, c1.x, c1.y}));
;                 oa0 = __builtin_amdgcn_mfma_f32_32x32x16_bf16(v0, pfa, oa0, 0, 0, 0);
;                 oa1 = __builtin_amdgcn_mfma_f32_32x32x16_bf16(v1, pfa, oa1, 0, 0, 0);
;                 ob0 = __builtin_amdgcn_mfma_f32_32x32x16_bf16(v0, pfb, ob0, 0, 0, 0);
;                 ob1 = __builtin_amdgcn_mfma_f32_32x32x16_bf16(v1, pfb, ob1, 0, 0, 0);
;             }
	v_mfma_f32_32x32x16_bf16 v[48:63], v[68:71], v[64:67], v[48:63]
	v_exp_f32_e32 v220, v72
	s_waitcnt lgkmcnt(0)
	v_mfma_f32_32x32x16_bf16 v[32:47], v[80:83], v[64:67], v[32:47]
	v_sub_f32_e32 v64, v79, v186
	v_exp_f32_e32 v221, v64
	v_cvt_pk_bf16_f32 v64, v216, v217
	v_cvt_pk_bf16_f32 v65, v219, v222
	v_cvt_pk_bf16_f32 v66, v223, v218
	v_cvt_pk_bf16_f32 v67, v220, v221
	s_nop 1
	s_nop 1
	v_mfma_f32_32x32x16_bf16 v[16:31], v[68:71], v[64:67], v[16:31]
	v_add_f32_e32 v68, v225, v224
	v_add_f32_e32 v68, v226, v68
	v_add_f32_e32 v68, v92, v68
	v_add_f32_e32 v68, v93, v68
	v_add_f32_e32 v68, v94, v68
	v_add_f32_e32 v68, v84, v68
	v_add_f32_e32 v185, v185, v68
	v_mfma_f32_32x32x16_bf16 v[0:15], v[80:83], v[64:67], v[0:15]
	s_setprio 1
	ds_read_b128 v[64:67], v187 offset:9216
	ds_read_b128 v[224:227], v187 offset:9248
	s_waitcnt lgkmcnt(1)
	v_mfma_f32_32x32x16_bf16 v[112:127], v[64:67], v[138:141], v[236:251]
	v_mfma_f32_32x32x16_bf16 v[96:111], v[64:67], v[146:149], 0
	ds_read_b128 v[64:67], v187 offset:13824
	s_waitcnt lgkmcnt(1)
	v_mfma_f32_32x32x16_bf16 v[112:127], v[224:227], v[142:145], v[112:127]
	v_mfma_f32_32x32x16_bf16 v[96:111], v[224:227], v[150:153], v[96:111]
	ds_read_b128 v[224:227], v187 offset:13856
	s_waitcnt lgkmcnt(1)
	v_mfma_f32_32x32x16_bf16 v[80:95], v[64:67], v[138:141], v[236:251]
	v_mfma_f32_32x32x16_bf16 v[64:79], v[64:67], v[146:149], 0
	s_waitcnt lgkmcnt(0)
	v_mfma_f32_32x32x16_bf16 v[80:95], v[224:227], v[142:145], v[80:95]
	v_mfma_f32_32x32x16_bf16 v[64:79], v[224:227], v[150:153], v[64:79]
	s_setprio 0
	s_nop 9
	v_max_f32_e32 v181, v112, v80
	v_max3_f32 v187, v81, v114, v82
	v_max3_f32 v181, v181, v113, v115
	v_max3_f32 v187, v187, v116, v84
	v_max3_f32 v181, v181, v83, v117
	v_max3_f32 v187, v187, v118, v86
	v_max3_f32 v181, v181, v85, v119
	v_max3_f32 v187, v187, v120, v88
	v_max3_f32 v181, v181, v87, v121
	v_max3_f32 v187, v187, v122, v90
	v_max3_f32 v181, v181, v89, v123
	v_max3_f32 v187, v187, v124, v92
	v_max3_f32 v181, v181, v91, v125
	v_max3_f32 v187, v187, v126, v94
	v_max3_f32 v181, v181, v93, v127
	v_max3_f32 v181, v181, v95, v187
	v_sub_f32_e32 v181, v181, v236
	ds_bpermute_b32 v187, v163, v181
	s_waitcnt lgkmcnt(0)
	v_max3_f32 v181, v188, v181, v187
	v_add_f32_e32 v187, 0x41000000, v188
	v_cmp_gt_f32_e32 vcc, v181, v187
	s_cbranch_vccz .LBB0_428
	v_add_f32_e32 v187, v181, v236
	v_sub_f32_e32 v112, v112, v187
	v_sub_f32_e32 v113, v113, v187
	v_sub_f32_e32 v114, v114, v187
	v_sub_f32_e32 v115, v115, v187
	v_sub_f32_e32 v116, v116, v187
	v_sub_f32_e32 v117, v117, v187
	v_sub_f32_e32 v118, v118, v187
	v_sub_f32_e32 v119, v119, v187
	v_sub_f32_e32 v120, v120, v187
	v_sub_f32_e32 v121, v121, v187
	v_sub_f32_e32 v122, v122, v187
	v_sub_f32_e32 v123, v123, v187
	v_sub_f32_e32 v124, v124, v187
	v_sub_f32_e32 v125, v125, v187
	v_sub_f32_e32 v126, v126, v187
	v_sub_f32_e32 v127, v127, v187
	v_sub_f32_e32 v80, v80, v187
	v_sub_f32_e32 v81, v81, v187
	v_sub_f32_e32 v82, v82, v187
	v_sub_f32_e32 v83, v83, v187
	v_sub_f32_e32 v84, v84, v187
	v_sub_f32_e32 v85, v85, v187
	v_sub_f32_e32 v86, v86, v187
	v_sub_f32_e32 v87, v87, v187
	v_sub_f32_e32 v88, v88, v187
	v_sub_f32_e32 v89, v89, v187
	v_sub_f32_e32 v90, v90, v187
	v_sub_f32_e32 v91, v91, v187
	v_sub_f32_e32 v92, v92, v187
	v_sub_f32_e32 v93, v93, v187
	v_sub_f32_e32 v94, v94, v187
	v_sub_f32_e32 v95, v95, v187
	v_sub_f32_e32 v236, 0, v181
	v_sub_f32_e32 v237, 0, v181
	v_sub_f32_e32 v238, 0, v181
	v_sub_f32_e32 v239, 0, v181
	v_sub_f32_e32 v240, 0, v181
	v_sub_f32_e32 v241, 0, v181
	v_sub_f32_e32 v242, 0, v181
	v_sub_f32_e32 v243, 0, v181
	v_sub_f32_e32 v244, 0, v181
	v_sub_f32_e32 v245, 0, v181
	v_sub_f32_e32 v246, 0, v181
	v_sub_f32_e32 v247, 0, v181
	v_sub_f32_e32 v248, 0, v181
	v_sub_f32_e32 v249, 0, v181
	v_sub_f32_e32 v250, 0, v181
	v_sub_f32_e32 v251, 0, v181
	v_sub_f32_e32 v187, v188, v181
	v_exp_f32_e32 v188, v187
	s_nop 0
	v_pk_mul_f32 v[62:63], v[62:63], v[188:189] op_sel_hi:[1,0]
	v_pk_mul_f32 v[60:61], v[60:61], v[188:189] op_sel_hi:[1,0]
	v_pk_mul_f32 v[58:59], v[58:59], v[188:189] op_sel_hi:[1,0]
	v_pk_mul_f32 v[56:57], v[56:57], v[188:189] op_sel_hi:[1,0]
	v_pk_mul_f32 v[54:55], v[54:55], v[188:189] op_sel_hi:[1,0]
	v_pk_mul_f32 v[52:53], v[52:53], v[188:189] op_sel_hi:[1,0]
	v_pk_mul_f32 v[50:51], v[50:51], v[188:189] op_sel_hi:[1,0]
	v_pk_mul_f32 v[48:49], v[48:49], v[188:189] op_sel_hi:[1,0]
	v_pk_mul_f32 v[46:47], v[46:47], v[188:189] op_sel_hi:[1,0]
	v_pk_mul_f32 v[44:45], v[44:45], v[188:189] op_sel_hi:[1,0]
	v_pk_mul_f32 v[42:43], v[42:43], v[188:189] op_sel_hi:[1,0]
	v_pk_mul_f32 v[40:41], v[40:41], v[188:189] op_sel_hi:[1,0]
	v_pk_mul_f32 v[38:39], v[38:39], v[188:189] op_sel_hi:[1,0]
	v_pk_mul_f32 v[36:37], v[36:37], v[188:189] op_sel_hi:[1,0]
	v_pk_mul_f32 v[34:35], v[34:35], v[188:189] op_sel_hi:[1,0]
	v_pk_mul_f32 v[32:33], v[32:33], v[188:189] op_sel_hi:[1,0]
	v_mul_f32_e32 v185, v185, v188
	s_branch .LBB0_429

; template <int DK, bool IS_A>
; __device__ __forceinline__ void attn_unit(const Params& P, int l, LAS unsigned char* lds, int b, int grp, int qtok0, int nkeys) {
;     ...
;             AT_SOFTMAX(pa, ma, la, oa0, oa1);
;             AT_SOFTMAX(pb, mb, lb_, ob0, ob1);
.LBB0_429:
	v_add_f32_e32 v184, v189, v184
	v_add_f32_e32 v184, v190, v184
	v_add_f32_e32 v184, v191, v184
	v_add_f32_e32 v184, v192, v184
	v_add_f32_e32 v184, v193, v184
	v_add_f32_e32 v184, v194, v184
	v_add_f32_e32 v184, v195, v184
	v_add_f32_e32 v184, v196, v184
	v_add_f32_e32 v184, v197, v184
	v_add_f32_e32 v184, v198, v184
	v_add_f32_e32 v184, v199, v184
	v_add_f32_e32 v184, v204, v184
	v_add_f32_e32 v184, v205, v184
	v_add_f32_e32 v184, v206, v184
	v_add_f32_e32 v184, v207, v184
	v_add_f32_e32 v184, v208, v184
	v_add_f32_e32 v184, v209, v184
	v_max_f32_e32 v187, v64, v64
	v_max_f32_e32 v188, v96, v96
	v_add_f32_e32 v184, v210, v184
	v_max_f32_e32 v187, v188, v187
	v_add_f32_e32 v184, v211, v184
	v_max3_f32 v188, v65, v98, v66
	v_max3_f32 v187, v187, v97, v99
	v_add_f32_e32 v184, v212, v184
	v_max3_f32 v188, v188, v100, v68
	v_max3_f32 v187, v187, v67, v101
	v_add_f32_e32 v184, v213, v184
	v_max3_f32 v188, v188, v102, v70
	v_max3_f32 v187, v187, v69, v103
	v_add_f32_e32 v184, v214, v184
	v_max3_f32 v188, v188, v104, v72
	v_max3_f32 v187, v187, v71, v105
	v_add_f32_e32 v184, v215, v184
	v_max3_f32 v188, v188, v106, v74
	v_max3_f32 v187, v187, v73, v107
	v_add_f32_e32 v184, v216, v184
	v_max3_f32 v188, v188, v108, v76
	v_max3_f32 v187, v187, v75, v109
	v_add_f32_e32 v184, v217, v184
	v_max3_f32 v188, v188, v110, v78
	v_max3_f32 v187, v187, v77, v111
	v_add_f32_e32 v184, v219, v184
	v_max3_f32 v187, v187, v79, v188
	v_add_f32_e32 v184, v222, v184
	ds_bpermute_b32 v188, v163, v187
	v_add_f32_e32 v184, v223, v184
	v_add_f32_e32 v184, v218, v184
	v_add_f32_e32 v184, v220, v184
	v_add_f32_e32 v184, v221, v184
	v_add_f32_e32 v180, v180, v184
	s_waitcnt lgkmcnt(0)
	v_max3_f32 v184, v186, v187, v188
	v_add_f32_e32 v188, 0x41000000, v186
	v_cmp_gt_f32_e32 vcc, v184, v188
	s_cbranch_vccz .LBB0_431
	v_sub_f32_e32 v186, v186, v184
	v_exp_f32_e32 v186, v186
	s_nop 0
	v_pk_mul_f32 v[30:31], v[30:31], v[186:187] op_sel_hi:[1,0]
	v_pk_mul_f32 v[28:29], v[28:29], v[186:187] op_sel_hi:[1,0]
	v_pk_mul_f32 v[26:27], v[26:27], v[186:187] op_sel_hi:[1,0]
	v_pk_mul_f32 v[24:25], v[24:25], v[186:187] op_sel_hi:[1,0]
	v_pk_mul_f32 v[22:23], v[22:23], v[186:187] op_sel_hi:[1,0]
	v_pk_mul_f32 v[20:21], v[20:21], v[186:187] op_sel_hi:[1,0]
	v_pk_mul_f32 v[18:19], v[18:19], v[186:187] op_sel_hi:[1,0]
	v_pk_mul_f32 v[16:17], v[16:17], v[186:187] op_sel_hi:[1,0]
	v_pk_mul_f32 v[14:15], v[14:15], v[186:187] op_sel_hi:[1,0]
	v_pk_mul_f32 v[12:13], v[12:13], v[186:187] op_sel_hi:[1,0]
	v_pk_mul_f32 v[10:11], v[10:11], v[186:187] op_sel_hi:[1,0]
	v_pk_mul_f32 v[8:9], v[8:9], v[186:187] op_sel_hi:[1,0]
	v_pk_mul_f32 v[6:7], v[6:7], v[186:187] op_sel_hi:[1,0]
	v_pk_mul_f32 v[4:5], v[4:5], v[186:187] op_sel_hi:[1,0]
	v_pk_mul_f32 v[2:3], v[2:3], v[186:187] op_sel_hi:[1,0]
	v_pk_mul_f32 v[0:1], v[0:1], v[186:187] op_sel_hi:[1,0]
	v_mul_f32_e32 v180, v180, v186
	s_branch .LBB0_432

; #define LAS __attribute__((address_space(3)))
; template <int DK, bool IS_A>
; __device__ __forceinline__ void attn_unit(const Params& P, int l, LAS unsigned char* lds, int b, int grp, int qtok0, int nkeys) {
;     ...
;             __builtin_amdgcn_s_setprio(1);
; #pragma unroll
;             for (int i = 0; i < DK / 16; ++i)
; #pragma unroll
;                 for (int jj = 0; jj < 2; ++jj) {
;                     const bf16x8 kf = *(const LAS bf16x8*)(kb + jj * 32 * AK_PITCH + i * 32);
;                     pa[jj] = __builtin_amdgcn_mfma_f32_32x32x16_bf16(kf, qa[i], pa[jj], 0, 0, 0);
;                     pb[jj] = __builtin_amdgcn_mfma_f32_32x32x16_bf16(kf, qb[i], pb[jj], 0, 0, 0);
;                 }
;             __builtin_amdgcn_s_setprio(0);
;     ...
;             AT_SOFTMAX(pa, ma, la, oa0, oa1);
;             AT_SOFTMAX(pb, mb, lb_, ob0, ob1);
.LBB0_445:
	s_mov_b32 s12, s100
	v_add_u32_e32 v64, s12, v178
	v_add_u32_e32 v199, v64, v192
	s_setprio 1
	ds_read_b128 v[64:67], v199
	ds_read_b128 v[204:207], v199 offset:32
	s_waitcnt lgkmcnt(1)
	v_mfma_f32_32x32x16_bf16 v[112:127], v[64:67], v[142:145], 0
	v_mfma_f32_32x32x16_bf16 v[96:111], v[64:67], v[146:149], 0
	ds_read_b128 v[64:67], v199 offset:4608
	s_waitcnt lgkmcnt(1)
	v_mfma_f32_32x32x16_bf16 v[112:127], v[204:207], v[154:157], v[112:127]
	v_mfma_f32_32x32x16_bf16 v[96:111], v[204:207], v[162:165], v[96:111]
	ds_read_b128 v[204:207], v199 offset:4640
	s_waitcnt lgkmcnt(1)
	v_mfma_f32_32x32x16_bf16 v[80:95], v[64:67], v[142:145], 0
	v_mfma_f32_32x32x16_bf16 v[64:79], v[64:67], v[146:149], 0
	s_waitcnt lgkmcnt(0)
	v_mfma_f32_32x32x16_bf16 v[80:95], v[204:207], v[154:157], v[80:95]
	v_mfma_f32_32x32x16_bf16 v[64:79], v[204:207], v[162:165], v[64:79]
	ds_read_b128 v[204:207], v199 offset:64
	s_waitcnt lgkmcnt(0)
	v_mfma_f32_32x32x16_bf16 v[112:127], v[204:207], v[158:161], v[112:127]
	v_mfma_f32_32x32x16_bf16 v[96:111], v[204:207], v[170:173], v[96:111]
	ds_read_b128 v[204:207], v199 offset:4672
	s_waitcnt lgkmcnt(0)
	v_mfma_f32_32x32x16_bf16 v[80:95], v[204:207], v[158:161], v[80:95]
	v_mfma_f32_32x32x16_bf16 v[64:79], v[204:207], v[170:173], v[64:79]
	ds_read_b128 v[204:207], v199 offset:96
	s_waitcnt lgkmcnt(0)
	v_mfma_f32_32x32x16_bf16 v[112:127], v[204:207], v[166:169], v[112:127]
	v_mfma_f32_32x32x16_bf16 v[96:111], v[204:207], v[174:177], v[96:111]
	ds_read_b128 v[204:207], v199 offset:4704
	s_waitcnt lgkmcnt(0)
	v_mfma_f32_32x32x16_bf16 v[80:95], v[204:207], v[166:169], v[80:95]
	v_mfma_f32_32x32x16_bf16 v[64:79], v[204:207], v[174:177], v[64:79]
	s_setprio 0
	s_nop 9
	v_max_f32_e32 v185, v112, v80
	v_max3_f32 v187, v81, v114, v82
	v_max3_f32 v185, v185, v113, v115
	v_max3_f32 v187, v187, v116, v84
	v_max3_f32 v185, v185, v83, v117
	v_max3_f32 v187, v187, v118, v86
	v_max3_f32 v185, v185, v85, v119
	v_max3_f32 v187, v187, v120, v88
	v_max3_f32 v185, v185, v87, v121
	v_max3_f32 v187, v187, v122, v90
	v_max3_f32 v185, v185, v89, v123
	v_max3_f32 v187, v187, v124, v92
	v_max3_f32 v185, v185, v91, v125
	v_max3_f32 v187, v187, v126, v94
	v_max3_f32 v185, v185, v93, v127
	v_max3_f32 v185, v185, v95, v187
	ds_bpermute_b32 v187, v181, v185
	s_waitcnt lgkmcnt(0)
	v_max3_f32 v205, v184, v185, v187
	v_add_f32_e32 v187, 0x41000000, v184
	v_cmp_gt_f32_e32 vcc, v205, v187
	s_cbranch_vccz .LBB0_447
	v_sub_f32_e32 v184, v184, v205
	v_exp_f32_e32 v184, v184
	s_nop 0
	v_pk_mul_f32 v[62:63], v[62:63], v[184:185] op_sel_hi:[1,0]
	v_pk_mul_f32 v[60:61], v[60:61], v[184:185] op_sel_hi:[1,0]
	v_pk_mul_f32 v[58:59], v[58:59], v[184:185] op_sel_hi:[1,0]
	v_pk_mul_f32 v[56:57], v[56:57], v[184:185] op_sel_hi:[1,0]
	v_pk_mul_f32 v[54:55], v[54:55], v[184:185] op_sel_hi:[1,0]
	v_pk_mul_f32 v[52:53], v[52:53], v[184:185] op_sel_hi:[1,0]
	v_pk_mul_f32 v[50:51], v[50:51], v[184:185] op_sel_hi:[1,0]
	v_pk_mul_f32 v[48:49], v[48:49], v[184:185] op_sel_hi:[1,0]
	v_pk_mul_f32 v[46:47], v[46:47], v[184:185] op_sel_hi:[1,0]
	v_pk_mul_f32 v[44:45], v[44:45], v[184:185] op_sel_hi:[1,0]
	v_pk_mul_f32 v[42:43], v[42:43], v[184:185] op_sel_hi:[1,0]
	v_pk_mul_f32 v[40:41], v[40:41], v[184:185] op_sel_hi:[1,0]
	v_pk_mul_f32 v[38:39], v[38:39], v[184:185] op_sel_hi:[1,0]
	v_pk_mul_f32 v[36:37], v[36:37], v[184:185] op_sel_hi:[1,0]
	v_pk_mul_f32 v[34:35], v[34:35], v[184:185] op_sel_hi:[1,0]
	v_pk_mul_f32 v[32:33], v[32:33], v[184:185] op_sel_hi:[1,0]
	v_mul_f32_e32 v198, v198, v184
	s_branch .LBB0_448

; template <int DK, bool IS_A>
; __device__ __forceinline__ void attn_unit(const Params& P, int l, LAS unsigned char* lds, int b, int grp, int qtok0, int nkeys) {
;     ...
;             AT_SOFTMAX(pa, ma, la, oa0, oa1);
;             AT_SOFTMAX(pb, mb, lb_, ob0, ob1);
.LBB0_448:
	v_max_f32_e32 v184, v96, v64
	v_max3_f32 v185, v65, v98, v66
	v_max3_f32 v184, v184, v97, v99
	v_max3_f32 v185, v185, v100, v68
	v_max3_f32 v184, v184, v67, v101
	v_max3_f32 v185, v185, v102, v70
	v_max3_f32 v184, v184, v69, v103
	v_max3_f32 v185, v185, v104, v72
	v_max3_f32 v184, v184, v71, v105
	v_max3_f32 v185, v185, v106, v74
	v_max3_f32 v184, v184, v73, v107
	v_max3_f32 v185, v185, v108, v76
	v_max3_f32 v184, v184, v75, v109
	v_max3_f32 v185, v185, v110, v78
	v_max3_f32 v184, v184, v77, v111
	v_max3_f32 v184, v184, v79, v185
	ds_bpermute_b32 v185, v181, v184
	s_waitcnt lgkmcnt(0)
	v_max3_f32 v204, v193, v184, v185
	v_add_f32_e32 v185, 0x41000000, v193
	v_cmp_gt_f32_e32 vcc, v204, v185
	s_cbranch_vccz .LBB0_450
	v_sub_f32_e32 v184, v193, v204
	v_exp_f32_e32 v184, v184
	s_nop 0
	v_pk_mul_f32 v[30:31], v[30:31], v[184:185] op_sel_hi:[1,0]
	v_pk_mul_f32 v[28:29], v[28:29], v[184:185] op_sel_hi:[1,0]
	v_pk_mul_f32 v[26:27], v[26:27], v[184:185] op_sel_hi:[1,0]
	v_pk_mul_f32 v[24:25], v[24:25], v[184:185] op_sel_hi:[1,0]
	v_pk_mul_f32 v[22:23], v[22:23], v[184:185] op_sel_hi:[1,0]
	v_pk_mul_f32 v[20:21], v[20:21], v[184:185] op_sel_hi:[1,0]
	v_pk_mul_f32 v[18:19], v[18:19], v[184:185] op_sel_hi:[1,0]
	v_pk_mul_f32 v[16:17], v[16:17], v[184:185] op_sel_hi:[1,0]
	v_pk_mul_f32 v[14:15], v[14:15], v[184:185] op_sel_hi:[1,0]
	v_pk_mul_f32 v[12:13], v[12:13], v[184:185] op_sel_hi:[1,0]
	v_pk_mul_f32 v[10:11], v[10:11], v[184:185] op_sel_hi:[1,0]
	v_pk_mul_f32 v[8:9], v[8:9], v[184:185] op_sel_hi:[1,0]
	v_pk_mul_f32 v[6:7], v[6:7], v[184:185] op_sel_hi:[1,0]
	v_pk_mul_f32 v[4:5], v[4:5], v[184:185] op_sel_hi:[1,0]
	v_pk_mul_f32 v[2:3], v[2:3], v[184:185] op_sel_hi:[1,0]
	v_pk_mul_f32 v[0:1], v[0:1], v[184:185] op_sel_hi:[1,0]
	v_mul_f32_e32 v183, v183, v184
	s_branch .LBB0_451

; #define LAS __attribute__((address_space(3)))
; __device__ __forceinline__ unsigned pk2(float lo, float hi) { f32x2_t v = {lo, hi}; bf16x2_t b = __builtin_convertvector(v, bf16x2_t); return __builtin_bit_cast(unsigned, b); }
; template <int DK, bool IS_A>
; __device__ __forceinline__ void attn_unit(const Params& P, int l, LAS unsigned char* lds, int b, int grp, int qtok0, int nkeys) {
;     ...
;             AT_SOFTMAX(pa, ma, la, oa0, oa1);
;             AT_SOFTMAX(pb, mb, lb_, ob0, ob1);
;     ...
; #pragma unroll
;             for (int ks = 0; ks < 4; ++ks) {
;                 const int o8 = 8 * (ks & 1);
;                 u32x4 w; const f32x16& xa = pa[ks >> 1]; const f32x16& xb = pb[ks >> 1];
;                 w.x = pk2(xa[o8], xa[o8 + 1]); w.y = pk2(xa[o8 + 2], xa[o8 + 3]); w.z = pk2(xa[o8 + 4], xa[o8 + 5]); w.w = pk2(xa[o8 + 6], xa[o8 + 7]);
;                 const bf16x8 pfa = __builtin_bit_cast(bf16x8, w);
;                 w.x = pk2(xb[o8], xb[o8 + 1]); w.y = pk2(xb[o8 + 2], xb[o8 + 3]); w.z = pk2(xb[o8 + 4], xb[o8 + 5]); w.w = pk2(xb[o8 + 6], xb[o8 + 7]);
;                 const bf16x8 pfb = __builtin_bit_cast(bf16x8, w);
;                 const u32x2 a0 = *(const LAS u32x2*)(vb + ks * 32), a1 = *(const LAS u32x2*)(vb + ks * 32 + 16);
;                 const u32x2 c0 = *(const LAS u32x2*)(vb + 32 * AV_PITCH + ks * 32), c1 = *(const LAS u32x2*)(vb + 32 * AV_PITCH + ks * 32 + 16);
;                 const bf16x8 v0 = __builtin_bit_cast(bf16x8, ((u32x4){a0.x, a0.y, a1.x, a1.y})), v1 = __builtin_bit_cast(bf16x8, ((u32x4){c0.x, c0.y, c1.x, c1.y}));
;                 oa0 = __builtin_amdgcn_mfma_f32_32x32x16_bf16(v0, pfa, oa0, 0, 0, 0);
;                 oa1 = __builtin_amdgcn_mfma_f32_32x32x16_bf16(v1, pfa, oa1, 0, 0, 0);
;                 ob0 = __builtin_amdgcn_mfma_f32_32x32x16_bf16(v0, pfb, ob0, 0, 0, 0);
;                 ob1 = __builtin_amdgcn_mfma_f32_32x32x16_bf16(v1, pfb, ob1, 0, 0, 0);
;             }
.LBB0_451:
	v_sub_f32_e32 v112, v112, v205
	v_exp_f32_e32 v112, v112
	v_sub_f32_e32 v113, v113, v205
	v_exp_f32_e32 v113, v113
	v_sub_f32_e32 v114, v114, v205
	v_exp_f32_e32 v114, v114
	v_sub_f32_e32 v115, v115, v205
	v_exp_f32_e32 v115, v115
	v_sub_f32_e32 v116, v116, v205
	v_exp_f32_e32 v116, v116
	v_sub_f32_e32 v117, v117, v205
	v_add_f32_e32 v184, v113, v112
	v_exp_f32_e32 v117, v117
	v_sub_f32_e32 v118, v118, v205
	v_add_f32_e32 v184, v114, v184
	v_exp_f32_e32 v118, v118
	v_sub_f32_e32 v119, v119, v205
	v_add_f32_e32 v184, v115, v184
	v_exp_f32_e32 v119, v119
	v_sub_f32_e32 v120, v120, v205
	v_add_f32_e32 v184, v116, v184
	v_exp_f32_e32 v120, v120
	v_sub_f32_e32 v121, v121, v205
	v_add_f32_e32 v184, v117, v184
	v_exp_f32_e32 v121, v121
	v_sub_f32_e32 v122, v122, v205
	v_add_f32_e32 v184, v118, v184
	v_exp_f32_e32 v122, v122
	v_sub_f32_e32 v123, v123, v205
	v_add_f32_e32 v184, v119, v184
	v_exp_f32_e32 v123, v123
	v_sub_f32_e32 v124, v124, v205
	v_add_f32_e32 v184, v120, v184
	v_exp_f32_e32 v124, v124
	v_sub_f32_e32 v125, v125, v205
	v_add_f32_e32 v184, v121, v184
	v_exp_f32_e32 v125, v125
	v_sub_f32_e32 v126, v126, v205
	v_add_f32_e32 v184, v122, v184
	v_exp_f32_e32 v126, v126
	v_sub_f32_e32 v127, v127, v205
	v_add_f32_e32 v184, v123, v184
	v_exp_f32_e32 v127, v127
	v_sub_f32_e32 v80, v80, v205
	v_add_f32_e32 v184, v124, v184
	v_exp_f32_e32 v224, v80
	v_sub_f32_e32 v80, v81, v205
	v_add_f32_e32 v184, v125, v184
	v_exp_f32_e32 v225, v80
	v_sub_f32_e32 v81, v82, v205
	v_add_f32_e32 v80, v126, v184
	v_exp_f32_e32 v184, v81
	v_sub_f32_e32 v81, v83, v205
	v_add_f32_e32 v80, v127, v80
	v_exp_f32_e32 v226, v81
	v_sub_f32_e32 v81, v84, v205
	v_add_f32_e32 v80, v224, v80
	v_exp_f32_e32 v227, v81
	v_sub_f32_e32 v81, v85, v205
	v_add_f32_e32 v80, v225, v80
	v_exp_f32_e32 v228, v81
	v_sub_f32_e32 v81, v86, v205
	v_add_f32_e32 v80, v184, v80
	v_exp_f32_e32 v229, v81
	v_sub_f32_e32 v81, v87, v205
	v_add_f32_e32 v80, v226, v80
	v_exp_f32_e32 v230, v81
	v_sub_f32_e32 v81, v88, v205
	v_add_f32_e32 v80, v227, v80
	v_exp_f32_e32 v231, v81
	v_sub_f32_e32 v81, v89, v205
	v_add_f32_e32 v80, v228, v80
	v_exp_f32_e32 v233, v81
	v_add_f32_e32 v80, v229, v80
	v_add_f32_e32 v80, v230, v80
	v_add_f32_e32 v80, v231, v80
	v_add_f32_e32 v237, v233, v80
	v_sub_f32_e32 v80, v90, v205
	v_exp_f32_e32 v238, v80
	v_sub_f32_e32 v80, v91, v205
	v_exp_f32_e32 v239, v80
	v_sub_f32_e32 v80, v92, v205
	v_exp_f32_e32 v92, v80
	v_add_u32_e32 v80, s12, v182
	v_sub_f32_e32 v81, v96, v204
	v_add_u32_e32 v88, v80, v186
	v_exp_f32_e32 v193, v81
	v_sub_f32_e32 v81, v97, v204
	v_add_u32_e32 v185, 0x4800, v88
	v_add_u32_e32 v187, 0x6800, v88
	v_exp_f32_e32 v206, v81
	ds_read2_b64 v[80:83], v185 offset1:2
	ds_read2_b64 v[88:91], v187 offset0:32 offset1:34
	v_sub_f32_e32 v96, v99, v204
	v_sub_f32_e32 v84, v98, v204
	v_exp_f32_e32 v208, v96
	v_sub_f32_e32 v96, v100, v204
	v_exp_f32_e32 v207, v84
	v_cvt_pk_bf16_f32 v84, v112, v113
	v_cvt_pk_bf16_f32 v85, v114, v115
	v_cvt_pk_bf16_f32 v86, v116, v117
	v_cvt_pk_bf16_f32 v87, v118, v119
	v_exp_f32_e32 v209, v96
	v_sub_f32_e32 v96, v101, v204
	s_waitcnt lgkmcnt(1)
	v_mfma_f32_32x32x16_bf16 v[48:63], v[80:83], v[84:87], v[48:63]
	v_exp_f32_e32 v210, v96
	v_sub_f32_e32 v96, v102, v204
	v_exp_f32_e32 v211, v96
	v_sub_f32_e32 v96, v107, v204
	v_exp_f32_e32 v216, v96
	v_sub_f32_e32 v96, v108, v204
	v_exp_f32_e32 v217, v96
	s_waitcnt lgkmcnt(0)
	v_mfma_f32_32x32x16_bf16 v[32:47], v[88:91], v[84:87], v[32:47]
	v_sub_f32_e32 v84, v103, v204
	v_exp_f32_e32 v212, v84
	v_cvt_pk_bf16_f32 v84, v193, v206
	v_cvt_pk_bf16_f32 v85, v207, v208
	v_cvt_pk_bf16_f32 v86, v209, v210
	v_cvt_pk_bf16_f32 v87, v211, v212
	v_sub_f32_e32 v96, v109, v204
	v_exp_f32_e32 v218, v96
	v_mfma_f32_32x32x16_bf16 v[16:31], v[80:83], v[84:87], v[16:31]
	v_sub_f32_e32 v80, v93, v205
	v_exp_f32_e32 v93, v80
	v_sub_f32_e32 v80, v104, v204
	v_exp_f32_e32 v213, v80
	v_sub_f32_e32 v80, v105, v204
	v_exp_f32_e32 v214, v80
	ds_read2_b64 v[80:83], v185 offset0:4 offset1:6
	v_mfma_f32_32x32x16_bf16 v[0:15], v[88:91], v[84:87], v[0:15]
	ds_read2_b64 v[88:91], v187 offset0:36 offset1:38
	v_sub_f32_e32 v84, v106, v204
	v_exp_f32_e32 v215, v84
	v_cvt_pk_bf16_f32 v84, v120, v121
	v_cvt_pk_bf16_f32 v85, v122, v123
	v_cvt_pk_bf16_f32 v86, v124, v125
	v_cvt_pk_bf16_f32 v87, v126, v127
	v_sub_f32_e32 v96, v110, v204
	v_exp_f32_e32 v219, v96
	s_waitcnt lgkmcnt(1)
	v_mfma_f32_32x32x16_bf16 v[48:63], v[80:83], v[84:87], v[48:63]
	v_sub_f32_e32 v64, v64, v204
	v_exp_f32_e32 v221, v64
	v_sub_f32_e32 v64, v65, v204
	v_exp_f32_e32 v222, v64
	v_sub_f32_e32 v64, v66, v204
	v_exp_f32_e32 v223, v64
	v_sub_f32_e32 v64, v67, v204
	s_waitcnt lgkmcnt(0)
	v_mfma_f32_32x32x16_bf16 v[32:47], v[88:91], v[84:87], v[32:47]
	v_sub_f32_e32 v84, v111, v204
	v_exp_f32_e32 v220, v84
	v_cvt_pk_bf16_f32 v84, v213, v214
	v_cvt_pk_bf16_f32 v85, v215, v216
	v_cvt_pk_bf16_f32 v86, v217, v218
	v_cvt_pk_bf16_f32 v87, v219, v220
	s_nop 1
	v_mfma_f32_32x32x16_bf16 v[16:31], v[80:83], v[84:87], v[16:31]
	v_sub_f32_e32 v80, v94, v205
	v_exp_f32_e32 v94, v80
	ds_read2_b64 v[80:83], v185 offset0:8 offset1:10
	v_mfma_f32_32x32x16_bf16 v[0:15], v[88:91], v[84:87], v[0:15]
	ds_read2_b64 v[88:91], v187 offset0:40 offset1:42
	v_cvt_pk_bf16_f32 v84, v224, v225
	v_exp_f32_e32 v224, v64
	v_sub_f32_e32 v64, v68, v204
	v_exp_f32_e32 v225, v64
	v_sub_f32_e32 v64, v69, v204
	v_cvt_pk_bf16_f32 v85, v184, v226
	v_exp_f32_e32 v226, v64
	v_sub_f32_e32 v64, v70, v204
	v_cvt_pk_bf16_f32 v86, v227, v228
	v_exp_f32_e32 v227, v64
	v_sub_f32_e32 v64, v71, v204
	v_exp_f32_e32 v228, v64
	v_cvt_pk_bf16_f32 v87, v229, v230
	v_sub_f32_e32 v68, v95, v205
	v_cvt_pk_bf16_f32 v64, v221, v222
	s_waitcnt lgkmcnt(1)
; #define LAS __attribute__((address_space(3)))
; template <int DK, bool IS_A>
; __device__ __forceinline__ void attn_unit(const Params& P, int l, LAS unsigned char* lds, int b, int grp, int qtok0, int nkeys) {
;     ...
;             __builtin_amdgcn_s_setprio(1);
; #pragma unroll
;             for (int i = 0; i < DK / 16; ++i)
; #pragma unroll
;                 for (int jj = 0; jj < 2; ++jj) {
;                     const bf16x8 kf = *(const LAS bf16x8*)(kb + jj * 32 * AK_PITCH + i * 32);
;                     pa[jj] = __builtin_amdgcn_mfma_f32_32x32x16_bf16(kf, qa[i], pa[jj], 0, 0, 0);
;                     pb[jj] = __builtin_amdgcn_mfma_f32_32x32x16_bf16(kf, qb[i], pb[jj], 0, 0, 0);
;                 }
;             __builtin_amdgcn_s_setprio(0);
;     ...
;             AT_SOFTMAX(pa, ma, la, oa0, oa1);
;             AT_SOFTMAX(pb, mb, lb_, ob0, ob1);
;     ...
; #pragma unroll
;             for (int ks = 0; ks < 4; ++ks) {
;                 const int o8 = 8 * (ks & 1);
;                 u32x4 w; const f32x16& xa = pa[ks >> 1]; const f32x16& xb = pb[ks >> 1];
;                 w.x = pk2(xa[o8], xa[o8 + 1]); w.y = pk2(xa[o8 + 2], xa[o8 + 3]); w.z = pk2(xa[o8 + 4], xa[o8 + 5]); w.w = pk2(xa[o8 + 6], xa[o8 + 7]);
;                 const bf16x8 pfa = __builtin_bit_cast(bf16x8, w);
;                 w.x = pk2(xb[o8], xb[o8 + 1]); w.y = pk2(xb[o8 + 2], xb[o8 + 3]); w.z = pk2(xb[o8 + 4], xb[o8 + 5]); w.w = pk2(xb[o8 + 6], xb[o8 + 7]);
;                 const bf16x8 pfb = __builtin_bit_cast(bf16x8, w);
;                 const u32x2 a0 = *(const LAS u32x2*)(vb + ks * 32), a1 = *(const LAS u32x2*)(vb + ks * 32 + 16);
;                 const u32x2 c0 = *(const LAS u32x2*)(vb + 32 * AV_PITCH + ks * 32), c1 = *(const LAS u32x2*)(vb + 32 * AV_PITCH + ks * 32 + 16);
;                 const bf16x8 v0 = __builtin_bit_cast(bf16x8, ((u32x4){a0.x, a0.y, a1.x, a1.y})), v1 = __builtin_bit_cast(bf16x8, ((u32x4){c0.x, c0.y, c1.x, c1.y}));
;                 oa0 = __builtin_amdgcn_mfma_f32_32x32x16_bf16(v0, pfa, oa0, 0, 0, 0);
;                 oa1 = __builtin_amdgcn_mfma_f32_32x32x16_bf16(v1, pfa, oa1, 0, 0, 0);
;                 ob0 = __builtin_amdgcn_mfma_f32_32x32x16_bf16(v0, pfb, ob0, 0, 0, 0);
;                 ob1 = __builtin_amdgcn_mfma_f32_32x32x16_bf16(v1, pfb, ob1, 0, 0, 0);
;             }
	v_mfma_f32_32x32x16_bf16 v[48:63], v[80:83], v[84:87], v[48:63]
	v_cvt_pk_bf16_f32 v65, v223, v224
	v_cvt_pk_bf16_f32 v66, v225, v226
	v_cvt_pk_bf16_f32 v67, v227, v228
	s_waitcnt lgkmcnt(0)
	v_mfma_f32_32x32x16_bf16 v[32:47], v[88:91], v[84:87], v[32:47]
	v_exp_f32_e32 v84, v68
	v_sub_f32_e32 v68, v72, v204
	v_exp_f32_e32 v229, v68
	v_sub_f32_e32 v68, v73, v204
	v_exp_f32_e32 v230, v68
	ds_read2_b64 v[68:71], v185 offset0:12 offset1:14
	v_sub_f32_e32 v72, v75, v204
	v_mfma_f32_32x32x16_bf16 v[16:31], v[80:83], v[64:67], v[16:31]
	ds_read2_b64 v[80:83], v187 offset0:44 offset1:46
	v_exp_f32_e32 v235, v72
	v_sub_f32_e32 v72, v76, v204
	v_exp_f32_e32 v236, v72
	v_sub_f32_e32 v72, v77, v204
	v_mfma_f32_32x32x16_bf16 v[0:15], v[88:91], v[64:67], v[0:15]
	v_sub_f32_e32 v64, v74, v204
	v_exp_f32_e32 v232, v64
	v_cvt_pk_bf16_f32 v64, v231, v233
	v_cvt_pk_bf16_f32 v65, v238, v239
	v_cvt_pk_bf16_f32 v66, v92, v93
	v_cvt_pk_bf16_f32 v67, v94, v84
	v_exp_f32_e32 v231, v72
	v_sub_f32_e32 v72, v78, v204
	s_waitcnt lgkmcnt(1)
	v_mfma_f32_32x32x16_bf16 v[48:63], v[68:71], v[64:67], v[48:63]
	v_exp_f32_e32 v233, v72
	s_waitcnt lgkmcnt(0)
	v_mfma_f32_32x32x16_bf16 v[32:47], v[80:83], v[64:67], v[32:47]
	v_sub_f32_e32 v64, v79, v204
	v_exp_f32_e32 v234, v64
	v_cvt_pk_bf16_f32 v64, v229, v230
	v_cvt_pk_bf16_f32 v65, v232, v235
	v_cvt_pk_bf16_f32 v66, v236, v231
	v_cvt_pk_bf16_f32 v67, v233, v234
	s_nop 1
	v_mfma_f32_32x32x16_bf16 v[16:31], v[68:71], v[64:67], v[16:31]
	v_add_f32_e32 v68, v238, v237
	v_add_f32_e32 v68, v239, v68
	v_add_f32_e32 v68, v92, v68
	v_add_f32_e32 v68, v93, v68
	v_add_f32_e32 v68, v94, v68
	v_add_f32_e32 v68, v84, v68
	v_add_f32_e32 v198, v198, v68
	v_mfma_f32_32x32x16_bf16 v[0:15], v[80:83], v[64:67], v[0:15]
	s_setprio 1
	ds_read_b128 v[64:67], v199 offset:9216
	ds_read_b128 v[238:241], v199 offset:9248
	s_waitcnt lgkmcnt(1)
	v_mfma_f32_32x32x16_bf16 v[112:127], v[64:67], v[142:145], 0
	v_mfma_f32_32x32x16_bf16 v[96:111], v[64:67], v[146:149], 0
	ds_read_b128 v[64:67], v199 offset:13824
	s_waitcnt lgkmcnt(1)
	v_mfma_f32_32x32x16_bf16 v[112:127], v[238:241], v[154:157], v[112:127]
	v_mfma_f32_32x32x16_bf16 v[96:111], v[238:241], v[162:165], v[96:111]
	ds_read_b128 v[238:241], v199 offset:13856
	s_waitcnt lgkmcnt(1)
	v_mfma_f32_32x32x16_bf16 v[80:95], v[64:67], v[142:145], 0
	v_mfma_f32_32x32x16_bf16 v[64:79], v[64:67], v[146:149], 0
	s_waitcnt lgkmcnt(0)
	v_mfma_f32_32x32x16_bf16 v[80:95], v[238:241], v[154:157], v[80:95]
	v_mfma_f32_32x32x16_bf16 v[64:79], v[238:241], v[162:165], v[64:79]
	ds_read_b128 v[238:241], v199 offset:9280
	s_waitcnt lgkmcnt(0)
	v_mfma_f32_32x32x16_bf16 v[112:127], v[238:241], v[158:161], v[112:127]
	v_mfma_f32_32x32x16_bf16 v[96:111], v[238:241], v[170:173], v[96:111]
	ds_read_b128 v[238:241], v199 offset:13888
	s_waitcnt lgkmcnt(0)
	v_mfma_f32_32x32x16_bf16 v[80:95], v[238:241], v[158:161], v[80:95]
	v_mfma_f32_32x32x16_bf16 v[64:79], v[238:241], v[170:173], v[64:79]
	ds_read_b128 v[238:241], v199 offset:9312
	s_waitcnt lgkmcnt(0)
	v_mfma_f32_32x32x16_bf16 v[112:127], v[238:241], v[166:169], v[112:127]
	v_mfma_f32_32x32x16_bf16 v[96:111], v[238:241], v[174:177], v[96:111]
	ds_read_b128 v[238:241], v199 offset:13920
	s_waitcnt lgkmcnt(0)
	v_mfma_f32_32x32x16_bf16 v[80:95], v[238:241], v[166:169], v[80:95]
	v_mfma_f32_32x32x16_bf16 v[64:79], v[238:241], v[174:177], v[64:79]
	s_setprio 0
	s_nop 9
	v_max_f32_e32 v184, v112, v80
	v_max3_f32 v199, v81, v114, v82
	v_max3_f32 v184, v184, v113, v115
	v_max3_f32 v199, v199, v116, v84
	v_max3_f32 v184, v184, v83, v117
	v_max3_f32 v199, v199, v118, v86
	v_max3_f32 v184, v184, v85, v119
	v_max3_f32 v199, v199, v120, v88
	v_max3_f32 v184, v184, v87, v121
	v_max3_f32 v199, v199, v122, v90
	v_max3_f32 v184, v184, v89, v123
	v_max3_f32 v199, v199, v124, v92
	v_max3_f32 v184, v184, v91, v125
	v_max3_f32 v199, v199, v126, v94
	v_max3_f32 v184, v184, v93, v127
	v_max3_f32 v184, v184, v95, v199
	ds_bpermute_b32 v199, v181, v184
	s_waitcnt lgkmcnt(0)
	v_max3_f32 v184, v205, v184, v199
	v_add_f32_e32 v199, 0x41000000, v205
	v_cmp_gt_f32_e32 vcc, v184, v199
	s_cbranch_vccz .LBB0_453
	v_sub_f32_e32 v199, v205, v184
	v_exp_f32_e32 v238, v199
	s_nop 0
	v_pk_mul_f32 v[62:63], v[62:63], v[238:239] op_sel_hi:[1,0]
	v_pk_mul_f32 v[60:61], v[60:61], v[238:239] op_sel_hi:[1,0]
	v_pk_mul_f32 v[58:59], v[58:59], v[238:239] op_sel_hi:[1,0]
	v_pk_mul_f32 v[56:57], v[56:57], v[238:239] op_sel_hi:[1,0]
	v_pk_mul_f32 v[54:55], v[54:55], v[238:239] op_sel_hi:[1,0]
	v_pk_mul_f32 v[52:53], v[52:53], v[238:239] op_sel_hi:[1,0]
	v_pk_mul_f32 v[50:51], v[50:51], v[238:239] op_sel_hi:[1,0]
	v_pk_mul_f32 v[48:49], v[48:49], v[238:239] op_sel_hi:[1,0]
	v_pk_mul_f32 v[46:47], v[46:47], v[238:239] op_sel_hi:[1,0]
	v_pk_mul_f32 v[44:45], v[44:45], v[238:239] op_sel_hi:[1,0]
	v_pk_mul_f32 v[42:43], v[42:43], v[238:239] op_sel_hi:[1,0]
	v_pk_mul_f32 v[40:41], v[40:41], v[238:239] op_sel_hi:[1,0]
	v_pk_mul_f32 v[38:39], v[38:39], v[238:239] op_sel_hi:[1,0]
	v_pk_mul_f32 v[36:37], v[36:37], v[238:239] op_sel_hi:[1,0]
	v_pk_mul_f32 v[34:35], v[34:35], v[238:239] op_sel_hi:[1,0]
	v_pk_mul_f32 v[32:33], v[32:33], v[238:239] op_sel_hi:[1,0]
	v_mul_f32_e32 v198, v198, v238
	s_branch .LBB0_454

; template <int DK, bool IS_A>
; __device__ __forceinline__ void attn_unit(const Params& P, int l, LAS unsigned char* lds, int b, int grp, int qtok0, int nkeys) {
;     ...
;             AT_SOFTMAX(pa, ma, la, oa0, oa1);
;             AT_SOFTMAX(pb, mb, lb_, ob0, ob1);
.LBB0_454:
	v_add_f32_e32 v193, v206, v193
	v_add_f32_e32 v193, v207, v193
	v_add_f32_e32 v193, v208, v193
	v_add_f32_e32 v193, v209, v193
	v_add_f32_e32 v193, v210, v193
	v_add_f32_e32 v193, v211, v193
	v_add_f32_e32 v193, v212, v193
	v_add_f32_e32 v193, v213, v193
	v_add_f32_e32 v193, v214, v193
	v_add_f32_e32 v193, v215, v193
	v_add_f32_e32 v193, v216, v193
	v_add_f32_e32 v193, v217, v193
	v_add_f32_e32 v193, v218, v193
	v_add_f32_e32 v193, v219, v193
	v_add_f32_e32 v193, v220, v193
	v_add_f32_e32 v193, v221, v193
	v_add_f32_e32 v193, v222, v193
	v_max_f32_e32 v199, v64, v64
	v_max_f32_e32 v205, v96, v96
	v_add_f32_e32 v193, v223, v193
	v_max_f32_e32 v199, v205, v199
	v_add_f32_e32 v193, v224, v193
	v_max3_f32 v205, v65, v98, v66
	v_max3_f32 v199, v199, v97, v99
	v_add_f32_e32 v193, v225, v193
	v_max3_f32 v205, v205, v100, v68
	v_max3_f32 v199, v199, v67, v101
	v_add_f32_e32 v193, v226, v193
	v_max3_f32 v205, v205, v102, v70
	v_max3_f32 v199, v199, v69, v103
	v_add_f32_e32 v193, v227, v193
	v_max3_f32 v205, v205, v104, v72
	v_max3_f32 v199, v199, v71, v105
	v_add_f32_e32 v193, v228, v193
	v_max3_f32 v205, v205, v106, v74
	v_max3_f32 v199, v199, v73, v107
	v_add_f32_e32 v193, v229, v193
	v_max3_f32 v205, v205, v108, v76
	v_max3_f32 v199, v199, v75, v109
	v_add_f32_e32 v193, v230, v193
	v_max3_f32 v205, v205, v110, v78
	v_max3_f32 v199, v199, v77, v111
	v_add_f32_e32 v193, v232, v193
	v_max3_f32 v199, v199, v79, v205
	v_add_f32_e32 v193, v235, v193
	ds_bpermute_b32 v205, v181, v199
	v_add_f32_e32 v193, v236, v193
	v_add_f32_e32 v193, v231, v193
	v_add_f32_e32 v193, v233, v193
	v_add_f32_e32 v193, v234, v193
	v_add_f32_e32 v183, v183, v193
	s_waitcnt lgkmcnt(0)
	v_max3_f32 v193, v204, v199, v205
	v_add_f32_e32 v205, 0x41000000, v204
	v_cmp_gt_f32_e32 vcc, v193, v205
	s_cbranch_vccz .LBB0_456
	v_sub_f32_e32 v199, v204, v193
	v_exp_f32_e32 v204, v199
	s_nop 0
	v_pk_mul_f32 v[30:31], v[30:31], v[204:205] op_sel_hi:[1,0]
	v_pk_mul_f32 v[28:29], v[28:29], v[204:205] op_sel_hi:[1,0]
	v_pk_mul_f32 v[26:27], v[26:27], v[204:205] op_sel_hi:[1,0]
	v_pk_mul_f32 v[24:25], v[24:25], v[204:205] op_sel_hi:[1,0]
	v_pk_mul_f32 v[22:23], v[22:23], v[204:205] op_sel_hi:[1,0]
	v_pk_mul_f32 v[20:21], v[20:21], v[204:205] op_sel_hi:[1,0]
	v_pk_mul_f32 v[18:19], v[18:19], v[204:205] op_sel_hi:[1,0]
	v_pk_mul_f32 v[16:17], v[16:17], v[204:205] op_sel_hi:[1,0]
	v_pk_mul_f32 v[14:15], v[14:15], v[204:205] op_sel_hi:[1,0]
	v_pk_mul_f32 v[12:13], v[12:13], v[204:205] op_sel_hi:[1,0]
	v_pk_mul_f32 v[10:11], v[10:11], v[204:205] op_sel_hi:[1,0]
	v_pk_mul_f32 v[8:9], v[8:9], v[204:205] op_sel_hi:[1,0]
	v_pk_mul_f32 v[6:7], v[6:7], v[204:205] op_sel_hi:[1,0]
	v_pk_mul_f32 v[4:5], v[4:5], v[204:205] op_sel_hi:[1,0]
	v_pk_mul_f32 v[2:3], v[2:3], v[204:205] op_sel_hi:[1,0]
	v_pk_mul_f32 v[0:1], v[0:1], v[204:205] op_sel_hi:[1,0]
	v_mul_f32_e32 v183, v183, v204
	s_branch .LBB0_457
